# v14 + K-loops: mid-block s_setprio 0/1 pair removed
# speedup vs baseline: 1.0005x; 1.0005x over previous
.Lg1_nopf:
	s_barrier
	v_mfma_f32_16x16x32_bf16 v[124:127], v[128:131], v[204:207], v[124:127]
	v_mfma_f32_16x16x32_bf16 v[120:123], v[136:139], v[204:207], v[120:123]
	v_mfma_f32_16x16x32_bf16 v[96:99], v[128:131], v[212:215], v[96:99]
	v_mfma_f32_16x16x32_bf16 v[88:91], v[136:139], v[212:215], v[88:91]
	v_mfma_f32_16x16x32_bf16 v[76:79], v[128:131], v[220:223], v[76:79]
	v_mfma_f32_16x16x32_bf16 v[72:75], v[136:139], v[220:223], v[72:75]
	v_mfma_f32_16x16x32_bf16 v[60:63], v[128:131], v[228:231], v[60:63]
	v_mfma_f32_16x16x32_bf16 v[108:111], v[136:139], v[228:231], v[108:111]
	v_mfma_f32_16x16x32_bf16 v[124:127], v[132:135], v[208:211], v[124:127]
	v_mfma_f32_16x16x32_bf16 v[120:123], v[158:161], v[208:211], v[120:123]
	v_mfma_f32_16x16x32_bf16 v[96:99], v[132:135], v[216:219], v[96:99]
	v_mfma_f32_16x16x32_bf16 v[88:91], v[158:161], v[216:219], v[88:91]
	v_mfma_f32_16x16x32_bf16 v[76:79], v[132:135], v[224:227], v[76:79]
	v_mfma_f32_16x16x32_bf16 v[72:75], v[158:161], v[224:227], v[72:75]
	v_mfma_f32_16x16x32_bf16 v[60:63], v[132:135], v[232:235], v[60:63]
	v_mfma_f32_16x16x32_bf16 v[108:111], v[158:161], v[232:235], v[108:111]
	v_mfma_f32_16x16x32_bf16 v[116:119], v[168:171], v[204:207], v[116:119]
	v_mfma_f32_16x16x32_bf16 v[112:115], v[196:199], v[204:207], v[112:115]
	v_mfma_f32_16x16x32_bf16 v[84:87], v[168:171], v[212:215], v[84:87]
	v_mfma_f32_16x16x32_bf16 v[80:83], v[196:199], v[212:215], v[80:83]
	v_mfma_f32_16x16x32_bf16 v[68:71], v[168:171], v[220:223], v[68:71]
	v_mfma_f32_16x16x32_bf16 v[64:67], v[196:199], v[220:223], v[64:67]
	v_mfma_f32_16x16x32_bf16 v[104:107], v[168:171], v[228:231], v[104:107]
	v_mfma_f32_16x16x32_bf16 v[56:59], v[196:199], v[228:231], v[56:59]
	v_mfma_f32_16x16x32_bf16 v[116:119], v[172:175], v[208:211], v[116:119]
	v_mfma_f32_16x16x32_bf16 v[112:115], v[200:203], v[208:211], v[112:115]
	v_mfma_f32_16x16x32_bf16 v[84:87], v[172:175], v[216:219], v[84:87]
	v_mfma_f32_16x16x32_bf16 v[80:83], v[200:203], v[216:219], v[80:83]
	v_mfma_f32_16x16x32_bf16 v[68:71], v[172:175], v[224:227], v[68:71]
	v_mfma_f32_16x16x32_bf16 v[64:67], v[200:203], v[224:227], v[64:67]
	v_mfma_f32_16x16x32_bf16 v[104:107], v[172:175], v[232:235], v[104:107]
	v_mfma_f32_16x16x32_bf16 v[56:59], v[200:203], v[232:235], v[56:59]
	s_barrier
	s_setprio 0
	s_add_i32 s87, s82, s23
	v_lshl_add_u64 v[162:163], s[66:67], 0, v[140:141]
	s_mov_b32 m0, s87
	ds_read_b128 v[204:207], v194 offset:16384
	ds_read_b128 v[208:211], v194 offset:17408
	ds_read_b128 v[212:215], v194 offset:18432
	ds_read_b128 v[216:219], v194 offset:19456
	ds_read_b128 v[220:223], v194 offset:20480
	ds_read_b128 v[224:227], v194 offset:21504
	ds_read_b128 v[228:231], v194 offset:22528
	ds_read_b128 v[232:235], v194 offset:23552
	global_load_lds_dwordx4 v[162:163], off
	s_add_i32 m0, s87, 0x2000
	s_add_u32 s88, s66, 0x40000
	v_lshl_add_u64 v[178:179], s[66:67], 0, v[142:143]
	s_addc_u32 s89, s67, 0
	s_add_i32 s87, s83, s23
	global_load_lds_dwordx4 v[178:179], off
	v_lshl_add_u64 v[184:185], s[88:89], 0, v[140:141]
	s_mov_b32 m0, s87
	v_lshl_add_u64 v[236:237], s[68:69], 0, v[142:143]
	global_load_lds_dwordx4 v[184:185], off
	v_lshl_add_u64 v[184:185], s[88:89], 0, v[142:143]
	s_add_i32 m0, s87, 0x2000
	s_nop 0
	global_load_lds_dwordx4 v[184:185], off
	v_lshl_add_u64 v[184:185], s[68:69], 0, v[140:141]
	s_mov_b32 m0, s70
	s_nop 0
	global_load_lds_dwordx4 v[184:185], off
	s_mov_b32 m0, s71
	s_nop 0
	global_load_lds_dwordx4 v[236:237], off
	s_waitcnt vmcnt(8)
	s_waitcnt lgkmcnt(0)
	s_setprio 1
	s_barrier
	v_mfma_f32_16x16x32_bf16 v[52:55], v[128:131], v[204:207], v[52:55]
	v_mfma_f32_16x16x32_bf16 v[48:51], v[136:139], v[204:207], v[48:51]
	v_mfma_f32_16x16x32_bf16 v[16:19], v[128:131], v[212:215], v[16:19]
	v_mfma_f32_16x16x32_bf16 v[8:11], v[136:139], v[212:215], v[8:11]
	v_mfma_f32_16x16x32_bf16 v[28:31], v[128:131], v[220:223], v[28:31]
	v_mfma_f32_16x16x32_bf16 v[24:27], v[136:139], v[220:223], v[24:27]
	v_mfma_f32_16x16x32_bf16 v[36:39], v[128:131], v[228:231], v[36:39]
	v_mfma_f32_16x16x32_bf16 v[100:103], v[136:139], v[228:231], v[100:103]
	v_mfma_f32_16x16x32_bf16 v[52:55], v[132:135], v[208:211], v[52:55]
	v_mfma_f32_16x16x32_bf16 v[48:51], v[158:161], v[208:211], v[48:51]
	v_mfma_f32_16x16x32_bf16 v[16:19], v[132:135], v[216:219], v[16:19]
	v_mfma_f32_16x16x32_bf16 v[8:11], v[158:161], v[216:219], v[8:11]
	v_mfma_f32_16x16x32_bf16 v[28:31], v[132:135], v[224:227], v[28:31]
	v_mfma_f32_16x16x32_bf16 v[24:27], v[158:161], v[224:227], v[24:27]
	v_mfma_f32_16x16x32_bf16 v[36:39], v[132:135], v[232:235], v[36:39]
	v_mfma_f32_16x16x32_bf16 v[100:103], v[158:161], v[232:235], v[100:103]
	v_mfma_f32_16x16x32_bf16 v[44:47], v[168:171], v[204:207], v[44:47]
	v_mfma_f32_16x16x32_bf16 v[40:43], v[196:199], v[204:207], v[40:43]
	v_mfma_f32_16x16x32_bf16 v[0:3], v[168:171], v[212:215], v[0:3]
	v_mfma_f32_16x16x32_bf16 v[4:7], v[196:199], v[212:215], v[4:7]
	v_mfma_f32_16x16x32_bf16 v[12:15], v[168:171], v[220:223], v[12:15]
	v_mfma_f32_16x16x32_bf16 v[20:23], v[196:199], v[220:223], v[20:23]
	v_mfma_f32_16x16x32_bf16 v[92:95], v[168:171], v[228:231], v[92:95]
	v_mfma_f32_16x16x32_bf16 v[32:35], v[196:199], v[228:231], v[32:35]
	v_mfma_f32_16x16x32_bf16 v[44:47], v[172:175], v[208:211], v[44:47]
	v_mfma_f32_16x16x32_bf16 v[40:43], v[200:203], v[208:211], v[40:43]
	v_mfma_f32_16x16x32_bf16 v[0:3], v[172:175], v[216:219], v[0:3]
	v_mfma_f32_16x16x32_bf16 v[4:7], v[200:203], v[216:219], v[4:7]
	v_mfma_f32_16x16x32_bf16 v[12:15], v[172:175], v[224:227], v[12:15]
	v_mfma_f32_16x16x32_bf16 v[20:23], v[200:203], v[224:227], v[20:23]
	v_mfma_f32_16x16x32_bf16 v[92:95], v[172:175], v[232:235], v[92:95]
	v_mfma_f32_16x16x32_bf16 v[32:35], v[200:203], v[232:235], v[32:35]
	s_barrier
	s_setprio 0
	s_add_i32 s87, 0, 0x18000
	s_add_i32 s88, 0, 0x1c000
	v_add_u32_e32 v158, s87, v167
	v_add_u32_e32 v164, s88, v167
	ds_read_b128 v[128:131], v158
	ds_read_b128 v[132:135], v158 offset:1024
	ds_read_b128 v[136:139], v158 offset:2048
	ds_read_b128 v[158:161], v158 offset:3072
	ds_read_b128 v[168:171], v164
	ds_read_b128 v[172:175], v164 offset:1024
	ds_read_b128 v[196:199], v164 offset:2048
	ds_read_b128 v[200:203], v164 offset:3072
	s_add_u32 s68, s68, 0x40000
	s_addc_u32 s69, s69, 0
	s_mov_b32 m0, s72
	v_lshl_add_u64 v[238:239], s[68:69], 0, v[140:141]
	ds_read_b128 v[204:207], v194 offset:32768
	ds_read_b128 v[208:211], v194 offset:33792
	ds_read_b128 v[212:215], v194 offset:34816
	ds_read_b128 v[216:219], v194 offset:35840
	ds_read_b128 v[220:223], v194 offset:36864
	ds_read_b128 v[224:227], v194 offset:37888
	ds_read_b128 v[228:231], v194 offset:38912
	ds_read_b128 v[232:235], v194 offset:39936
	global_load_lds_dwordx4 v[238:239], off
	v_lshl_add_u64 v[238:239], s[68:69], 0, v[142:143]
	s_mov_b32 m0, s73
	s_nop 0
	global_load_lds_dwordx4 v[238:239], off
	s_waitcnt vmcnt(8)
	s_waitcnt lgkmcnt(0)
	s_setprio 1
	s_barrier
	v_mfma_f32_16x16x32_bf16 v[124:127], v[128:131], v[204:207], v[124:127]
	v_mfma_f32_16x16x32_bf16 v[120:123], v[136:139], v[204:207], v[120:123]
	v_mfma_f32_16x16x32_bf16 v[96:99], v[128:131], v[212:215], v[96:99]
	v_mfma_f32_16x16x32_bf16 v[88:91], v[136:139], v[212:215], v[88:91]
	v_mfma_f32_16x16x32_bf16 v[76:79], v[128:131], v[220:223], v[76:79]
	v_mfma_f32_16x16x32_bf16 v[72:75], v[136:139], v[220:223], v[72:75]
	v_mfma_f32_16x16x32_bf16 v[60:63], v[128:131], v[228:231], v[60:63]
	v_mfma_f32_16x16x32_bf16 v[108:111], v[136:139], v[228:231], v[108:111]
	v_mfma_f32_16x16x32_bf16 v[124:127], v[132:135], v[208:211], v[124:127]
	v_mfma_f32_16x16x32_bf16 v[120:123], v[158:161], v[208:211], v[120:123]
	v_mfma_f32_16x16x32_bf16 v[96:99], v[132:135], v[216:219], v[96:99]
	v_mfma_f32_16x16x32_bf16 v[88:91], v[158:161], v[216:219], v[88:91]
	v_mfma_f32_16x16x32_bf16 v[76:79], v[132:135], v[224:227], v[76:79]
	v_mfma_f32_16x16x32_bf16 v[72:75], v[158:161], v[224:227], v[72:75]
	v_mfma_f32_16x16x32_bf16 v[60:63], v[132:135], v[232:235], v[60:63]
	v_mfma_f32_16x16x32_bf16 v[108:111], v[158:161], v[232:235], v[108:111]
	v_mfma_f32_16x16x32_bf16 v[116:119], v[168:171], v[204:207], v[116:119]
	v_mfma_f32_16x16x32_bf16 v[112:115], v[196:199], v[204:207], v[112:115]
	v_mfma_f32_16x16x32_bf16 v[84:87], v[168:171], v[212:215], v[84:87]
	v_mfma_f32_16x16x32_bf16 v[80:83], v[196:199], v[212:215], v[80:83]
	v_mfma_f32_16x16x32_bf16 v[68:71], v[168:171], v[220:223], v[68:71]
	v_mfma_f32_16x16x32_bf16 v[64:67], v[196:199], v[220:223], v[64:67]
	v_mfma_f32_16x16x32_bf16 v[104:107], v[168:171], v[228:231], v[104:107]
	v_mfma_f32_16x16x32_bf16 v[56:59], v[196:199], v[228:231], v[56:59]
	v_mfma_f32_16x16x32_bf16 v[116:119], v[172:175], v[208:211], v[116:119]
	v_mfma_f32_16x16x32_bf16 v[112:115], v[200:203], v[208:211], v[112:115]
	v_mfma_f32_16x16x32_bf16 v[84:87], v[172:175], v[216:219], v[84:87]
	v_mfma_f32_16x16x32_bf16 v[80:83], v[200:203], v[216:219], v[80:83]
	v_mfma_f32_16x16x32_bf16 v[68:71], v[172:175], v[224:227], v[68:71]
	v_mfma_f32_16x16x32_bf16 v[64:67], v[200:203], v[224:227], v[64:67]
	v_mfma_f32_16x16x32_bf16 v[104:107], v[172:175], v[232:235], v[104:107]
	v_mfma_f32_16x16x32_bf16 v[56:59], v[200:203], v[232:235], v[56:59]
	s_barrier
	s_setprio 0
	s_add_i32 s68, s87, s23
	v_lshl_add_u64 v[162:163], v[162:163], 0, s[36:37]
	s_mov_b32 m0, s68
	ds_read_b128 v[204:207], v194 offset:49152
	ds_read_b128 v[208:211], v194 offset:50176
	ds_read_b128 v[212:215], v194 offset:51200
	ds_read_b128 v[216:219], v194 offset:52224
	ds_read_b128 v[220:223], v194 offset:53248
	ds_read_b128 v[224:227], v194 offset:54272
	ds_read_b128 v[228:231], v194 offset:55296
	ds_read_b128 v[232:235], v194 offset:56320
	global_load_lds_dwordx4 v[162:163], off
	s_add_i32 m0, s68, 0x2000
	s_add_u32 s66, s66, 0x40080
	v_lshl_add_u64 v[162:163], v[178:179], 0, s[36:37]
	s_addc_u32 s67, s67, 0
	s_add_i32 s68, s88, s23
	global_load_lds_dwordx4 v[162:163], off
	v_lshl_add_u64 v[162:163], s[66:67], 0, v[140:141]
	s_mov_b32 m0, s68
	s_nop 0
	global_load_lds_dwordx4 v[162:163], off
	v_lshl_add_u64 v[162:163], s[66:67], 0, v[142:143]
	s_add_i32 m0, s68, 0x2000
	s_nop 0
	global_load_lds_dwordx4 v[162:163], off
	v_lshl_add_u64 v[162:163], v[184:185], 0, s[36:37]
	s_mov_b32 m0, s80
	s_nop 0
	global_load_lds_dwordx4 v[162:163], off
	v_lshl_add_u64 v[162:163], v[236:237], 0, s[36:37]
	s_mov_b32 m0, s81
	s_nop 0
	global_load_lds_dwordx4 v[162:163], off
	s_waitcnt vmcnt(8)
	s_waitcnt lgkmcnt(0)
	s_setprio 1
	s_barrier
	v_mfma_f32_16x16x32_bf16 v[52:55], v[128:131], v[204:207], v[52:55]
	v_mfma_f32_16x16x32_bf16 v[48:51], v[136:139], v[204:207], v[48:51]
	v_mfma_f32_16x16x32_bf16 v[16:19], v[128:131], v[212:215], v[16:19]
	v_mfma_f32_16x16x32_bf16 v[8:11], v[136:139], v[212:215], v[8:11]
	v_mfma_f32_16x16x32_bf16 v[28:31], v[128:131], v[220:223], v[28:31]
	v_mfma_f32_16x16x32_bf16 v[24:27], v[136:139], v[220:223], v[24:27]
	v_mfma_f32_16x16x32_bf16 v[36:39], v[128:131], v[228:231], v[36:39]
	v_mfma_f32_16x16x32_bf16 v[100:103], v[136:139], v[228:231], v[100:103]
	v_mfma_f32_16x16x32_bf16 v[52:55], v[132:135], v[208:211], v[52:55]
	v_mfma_f32_16x16x32_bf16 v[48:51], v[158:161], v[208:211], v[48:51]
	v_mfma_f32_16x16x32_bf16 v[16:19], v[132:135], v[216:219], v[16:19]
	v_mfma_f32_16x16x32_bf16 v[8:11], v[158:161], v[216:219], v[8:11]
	v_mfma_f32_16x16x32_bf16 v[28:31], v[132:135], v[224:227], v[28:31]
	v_mfma_f32_16x16x32_bf16 v[24:27], v[158:161], v[224:227], v[24:27]
	v_mfma_f32_16x16x32_bf16 v[36:39], v[132:135], v[232:235], v[36:39]
	v_mfma_f32_16x16x32_bf16 v[100:103], v[158:161], v[232:235], v[100:103]
	v_mfma_f32_16x16x32_bf16 v[44:47], v[168:171], v[204:207], v[44:47]
	v_mfma_f32_16x16x32_bf16 v[40:43], v[196:199], v[204:207], v[40:43]
	v_mfma_f32_16x16x32_bf16 v[0:3], v[168:171], v[212:215], v[0:3]
	v_mfma_f32_16x16x32_bf16 v[4:7], v[196:199], v[212:215], v[4:7]
	v_mfma_f32_16x16x32_bf16 v[12:15], v[168:171], v[220:223], v[12:15]
	v_mfma_f32_16x16x32_bf16 v[20:23], v[196:199], v[220:223], v[20:23]
	v_mfma_f32_16x16x32_bf16 v[92:95], v[168:171], v[228:231], v[92:95]
	v_mfma_f32_16x16x32_bf16 v[32:35], v[196:199], v[228:231], v[32:35]
	v_mfma_f32_16x16x32_bf16 v[44:47], v[172:175], v[208:211], v[44:47]
	v_mfma_f32_16x16x32_bf16 v[40:43], v[200:203], v[208:211], v[40:43]
	v_mfma_f32_16x16x32_bf16 v[0:3], v[172:175], v[216:219], v[0:3]
	v_mfma_f32_16x16x32_bf16 v[4:7], v[200:203], v[216:219], v[4:7]
	v_mfma_f32_16x16x32_bf16 v[12:15], v[172:175], v[224:227], v[12:15]
	v_mfma_f32_16x16x32_bf16 v[20:23], v[200:203], v[224:227], v[20:23]
	v_mfma_f32_16x16x32_bf16 v[92:95], v[172:175], v[232:235], v[92:95]
	v_mfma_f32_16x16x32_bf16 v[32:35], v[200:203], v[232:235], v[32:35]
	s_barrier
	s_setprio 0
	s_add_i32 s86, s86, 2
	s_add_u32 s64, s64, 0x100
	s_addc_u32 s65, s65, 0
	s_add_u32 s84, s84, 0x100
	s_addc_u32 s85, s85, 0
	s_cmp_gt_u32 s86, 13
	s_cbranch_scc0 .LBB0_439
	s_and_b64 vcc, exec, s[38:39]
	s_cbranch_vccz .LBB0_442
	s_barrier

.LBB0_504:
	ds_read_b128 v[104:107], v200
	ds_read_b128 v[108:111], v200 offset:1024
	ds_read_b128 v[124:127], v200 offset:2048
	ds_read_b128 v[128:131], v200 offset:3072
	ds_read_b128 v[144:147], v201
	ds_read_b128 v[148:151], v201 offset:1024
	ds_read_b128 v[152:155], v201 offset:2048
	ds_read_b128 v[156:159], v201 offset:3072
	s_add_u32 s48, s46, 0xfffc0080
	s_addc_u32 s49, s47, -1
	s_cmp_eq_u32 s87, 12
	s_cselect_b32 s51, s39, s49
	s_cselect_b32 s50, s45, s48
	s_cselect_b32 s49, s37, s86
	s_cselect_b32 s48, s84, s85
	v_lshl_add_u64 v[196:197], s[46:47], 0, v[188:189]
	s_add_i32 m0, s52, 0xc000
	ds_read_b128 v[160:163], v202
	ds_read_b128 v[164:167], v202 offset:1024
	ds_read_b128 v[168:171], v202 offset:2048
	ds_read_b128 v[172:175], v202 offset:3072
	ds_read_b128 v[176:179], v202 offset:4096
	ds_read_b128 v[180:183], v202 offset:5120
	ds_read_b128 v[206:209], v202 offset:6144
	ds_read_b128 v[210:213], v202 offset:7168
	global_load_lds_dwordx4 v[196:197], off
	v_lshl_add_u64 v[196:197], s[46:47], 0, v[190:191]
	s_add_i32 m0, s52, 0xe000
	s_nop 0
	global_load_lds_dwordx4 v[196:197], off
	s_waitcnt vmcnt(8)
	s_waitcnt lgkmcnt(0)
	s_setprio 1
	s_barrier
	v_mfma_f32_16x16x32_bf16 v[140:143], v[104:107], v[160:163], v[140:143]
	v_mfma_f32_16x16x32_bf16 v[136:139], v[124:127], v[160:163], v[136:139]
	v_mfma_f32_16x16x32_bf16 v[116:119], v[104:107], v[168:171], v[116:119]
	v_mfma_f32_16x16x32_bf16 v[112:115], v[124:127], v[168:171], v[112:115]
	v_mfma_f32_16x16x32_bf16 v[92:95], v[104:107], v[176:179], v[92:95]
	v_mfma_f32_16x16x32_bf16 v[88:91], v[124:127], v[176:179], v[88:91]
	v_mfma_f32_16x16x32_bf16 v[76:79], v[104:107], v[206:209], v[76:79]
	v_mfma_f32_16x16x32_bf16 v[72:75], v[124:127], v[206:209], v[72:75]
	v_mfma_f32_16x16x32_bf16 v[140:143], v[108:111], v[164:167], v[140:143]
	v_mfma_f32_16x16x32_bf16 v[136:139], v[128:131], v[164:167], v[136:139]
	v_mfma_f32_16x16x32_bf16 v[116:119], v[108:111], v[172:175], v[116:119]
	v_mfma_f32_16x16x32_bf16 v[112:115], v[128:131], v[172:175], v[112:115]
	v_mfma_f32_16x16x32_bf16 v[92:95], v[108:111], v[180:183], v[92:95]
	v_mfma_f32_16x16x32_bf16 v[88:91], v[128:131], v[180:183], v[88:91]
	v_mfma_f32_16x16x32_bf16 v[76:79], v[108:111], v[210:213], v[76:79]
	v_mfma_f32_16x16x32_bf16 v[72:75], v[128:131], v[210:213], v[72:75]
	v_mfma_f32_16x16x32_bf16 v[132:135], v[144:147], v[160:163], v[132:135]
	v_mfma_f32_16x16x32_bf16 v[120:123], v[152:155], v[160:163], v[120:123]
	v_mfma_f32_16x16x32_bf16 v[100:103], v[144:147], v[168:171], v[100:103]
	v_mfma_f32_16x16x32_bf16 v[96:99], v[152:155], v[168:171], v[96:99]
	v_mfma_f32_16x16x32_bf16 v[84:87], v[144:147], v[176:179], v[84:87]
	v_mfma_f32_16x16x32_bf16 v[80:83], v[152:155], v[176:179], v[80:83]
	v_mfma_f32_16x16x32_bf16 v[68:71], v[144:147], v[206:209], v[68:71]
	v_mfma_f32_16x16x32_bf16 v[64:67], v[152:155], v[206:209], v[64:67]
	v_mfma_f32_16x16x32_bf16 v[132:135], v[148:151], v[164:167], v[132:135]
	v_mfma_f32_16x16x32_bf16 v[120:123], v[156:159], v[164:167], v[120:123]
	v_mfma_f32_16x16x32_bf16 v[100:103], v[148:151], v[172:175], v[100:103]
	v_mfma_f32_16x16x32_bf16 v[96:99], v[156:159], v[172:175], v[96:99]
	v_mfma_f32_16x16x32_bf16 v[84:87], v[148:151], v[180:183], v[84:87]
	v_mfma_f32_16x16x32_bf16 v[80:83], v[156:159], v[180:183], v[80:83]
	v_mfma_f32_16x16x32_bf16 v[68:71], v[148:151], v[210:213], v[68:71]
	v_mfma_f32_16x16x32_bf16 v[64:67], v[156:159], v[210:213], v[64:67]
	s_barrier
	s_setprio 0
	s_add_i32 s88, s69, s13
	v_lshl_add_u64 v[196:197], s[48:49], 0, v[184:185]
	s_mov_b32 m0, s88
	ds_read_b128 v[160:163], v202 offset:16384
	ds_read_b128 v[164:167], v202 offset:17408
	ds_read_b128 v[168:171], v202 offset:18432
	ds_read_b128 v[172:175], v202 offset:19456
	ds_read_b128 v[176:179], v202 offset:20480
	ds_read_b128 v[180:183], v202 offset:21504
	ds_read_b128 v[206:209], v202 offset:22528
	ds_read_b128 v[210:213], v202 offset:23552
	global_load_lds_dwordx4 v[196:197], off
	s_add_i32 m0, s88, 0x2000
	s_add_u32 s88, s48, 0x40000
	v_lshl_add_u64 v[214:215], s[48:49], 0, v[186:187]
	s_addc_u32 s89, s49, 0
	s_add_i32 s90, s70, s13
	global_load_lds_dwordx4 v[214:215], off
	v_lshl_add_u64 v[216:217], s[88:89], 0, v[184:185]
	s_mov_b32 m0, s90
	v_lshl_add_u64 v[218:219], s[50:51], 0, v[186:187]
	global_load_lds_dwordx4 v[216:217], off
	v_lshl_add_u64 v[216:217], s[88:89], 0, v[186:187]
	s_add_i32 m0, s90, 0x2000
	s_nop 0
	global_load_lds_dwordx4 v[216:217], off
	v_lshl_add_u64 v[216:217], s[50:51], 0, v[184:185]
	s_mov_b32 m0, s52
	s_nop 0
	global_load_lds_dwordx4 v[216:217], off
	s_mov_b32 m0, s53
	s_nop 0
	global_load_lds_dwordx4 v[218:219], off
	s_waitcnt vmcnt(8)
	s_waitcnt lgkmcnt(0)
	s_setprio 1
	s_barrier
	v_mfma_f32_16x16x32_bf16 v[60:63], v[104:107], v[160:163], v[60:63]
	v_mfma_f32_16x16x32_bf16 v[56:59], v[124:127], v[160:163], v[56:59]
	v_mfma_f32_16x16x32_bf16 v[44:47], v[104:107], v[168:171], v[44:47]
	v_mfma_f32_16x16x32_bf16 v[40:43], v[124:127], v[168:171], v[40:43]
	v_mfma_f32_16x16x32_bf16 v[28:31], v[104:107], v[176:179], v[28:31]
	v_mfma_f32_16x16x32_bf16 v[24:27], v[124:127], v[176:179], v[24:27]
	v_mfma_f32_16x16x32_bf16 v[12:15], v[104:107], v[206:209], v[12:15]
	v_mfma_f32_16x16x32_bf16 v[8:11], v[124:127], v[206:209], v[8:11]
	v_mfma_f32_16x16x32_bf16 v[60:63], v[108:111], v[164:167], v[60:63]
	v_mfma_f32_16x16x32_bf16 v[56:59], v[128:131], v[164:167], v[56:59]
	v_mfma_f32_16x16x32_bf16 v[44:47], v[108:111], v[172:175], v[44:47]
	v_mfma_f32_16x16x32_bf16 v[40:43], v[128:131], v[172:175], v[40:43]
	v_mfma_f32_16x16x32_bf16 v[28:31], v[108:111], v[180:183], v[28:31]
	v_mfma_f32_16x16x32_bf16 v[24:27], v[128:131], v[180:183], v[24:27]
	v_mfma_f32_16x16x32_bf16 v[12:15], v[108:111], v[210:213], v[12:15]
	v_mfma_f32_16x16x32_bf16 v[8:11], v[128:131], v[210:213], v[8:11]
	v_mfma_f32_16x16x32_bf16 v[52:55], v[144:147], v[160:163], v[52:55]
	v_mfma_f32_16x16x32_bf16 v[48:51], v[152:155], v[160:163], v[48:51]
	v_mfma_f32_16x16x32_bf16 v[36:39], v[144:147], v[168:171], v[36:39]
	v_mfma_f32_16x16x32_bf16 v[32:35], v[152:155], v[168:171], v[32:35]
	v_mfma_f32_16x16x32_bf16 v[20:23], v[144:147], v[176:179], v[20:23]
	v_mfma_f32_16x16x32_bf16 v[16:19], v[152:155], v[176:179], v[16:19]
	v_mfma_f32_16x16x32_bf16 v[4:7], v[144:147], v[206:209], v[4:7]
	v_mfma_f32_16x16x32_bf16 v[0:3], v[152:155], v[206:209], v[0:3]
	v_mfma_f32_16x16x32_bf16 v[52:55], v[148:151], v[164:167], v[52:55]
	v_mfma_f32_16x16x32_bf16 v[48:51], v[156:159], v[164:167], v[48:51]
	v_mfma_f32_16x16x32_bf16 v[36:39], v[148:151], v[172:175], v[36:39]
	v_mfma_f32_16x16x32_bf16 v[32:35], v[156:159], v[172:175], v[32:35]
	v_mfma_f32_16x16x32_bf16 v[20:23], v[148:151], v[180:183], v[20:23]
	v_mfma_f32_16x16x32_bf16 v[16:19], v[156:159], v[180:183], v[16:19]
	v_mfma_f32_16x16x32_bf16 v[4:7], v[148:151], v[210:213], v[4:7]
	v_mfma_f32_16x16x32_bf16 v[0:3], v[156:159], v[210:213], v[0:3]
	s_barrier
	s_setprio 0
	s_add_i32 s88, 0, 0x18000
	s_add_i32 s89, 0, 0x1c000
	v_add_u32_e32 v128, s88, v199
	v_add_u32_e32 v156, s89, v199
	ds_read_b128 v[104:107], v128
	ds_read_b128 v[108:111], v128 offset:1024
	ds_read_b128 v[124:127], v128 offset:2048
	ds_read_b128 v[128:131], v128 offset:3072
	ds_read_b128 v[144:147], v156
	ds_read_b128 v[148:151], v156 offset:1024
	ds_read_b128 v[152:155], v156 offset:2048
	ds_read_b128 v[156:159], v156 offset:3072
	s_add_u32 s50, s50, 0x40000
	s_addc_u32 s51, s51, 0
	s_mov_b32 m0, s54
	v_lshl_add_u64 v[220:221], s[50:51], 0, v[184:185]
	ds_read_b128 v[160:163], v202 offset:32768
	ds_read_b128 v[164:167], v202 offset:33792
	ds_read_b128 v[168:171], v202 offset:34816
	ds_read_b128 v[172:175], v202 offset:35840
	ds_read_b128 v[176:179], v202 offset:36864
	ds_read_b128 v[180:183], v202 offset:37888
	ds_read_b128 v[206:209], v202 offset:38912
	ds_read_b128 v[210:213], v202 offset:39936
	global_load_lds_dwordx4 v[220:221], off
	v_lshl_add_u64 v[220:221], s[50:51], 0, v[186:187]
	s_mov_b32 m0, s55
	s_nop 0
	global_load_lds_dwordx4 v[220:221], off
	s_waitcnt vmcnt(8)
	s_waitcnt lgkmcnt(0)
	s_setprio 1
	s_barrier
	v_mfma_f32_16x16x32_bf16 v[140:143], v[104:107], v[160:163], v[140:143]
	v_mfma_f32_16x16x32_bf16 v[136:139], v[124:127], v[160:163], v[136:139]
	v_mfma_f32_16x16x32_bf16 v[116:119], v[104:107], v[168:171], v[116:119]
	v_mfma_f32_16x16x32_bf16 v[112:115], v[124:127], v[168:171], v[112:115]
	v_mfma_f32_16x16x32_bf16 v[92:95], v[104:107], v[176:179], v[92:95]
	v_mfma_f32_16x16x32_bf16 v[88:91], v[124:127], v[176:179], v[88:91]
	v_mfma_f32_16x16x32_bf16 v[76:79], v[104:107], v[206:209], v[76:79]
	v_mfma_f32_16x16x32_bf16 v[72:75], v[124:127], v[206:209], v[72:75]
	v_mfma_f32_16x16x32_bf16 v[140:143], v[108:111], v[164:167], v[140:143]
	v_mfma_f32_16x16x32_bf16 v[136:139], v[128:131], v[164:167], v[136:139]
	v_mfma_f32_16x16x32_bf16 v[116:119], v[108:111], v[172:175], v[116:119]
	v_mfma_f32_16x16x32_bf16 v[112:115], v[128:131], v[172:175], v[112:115]
	v_mfma_f32_16x16x32_bf16 v[92:95], v[108:111], v[180:183], v[92:95]
	v_mfma_f32_16x16x32_bf16 v[88:91], v[128:131], v[180:183], v[88:91]
	v_mfma_f32_16x16x32_bf16 v[76:79], v[108:111], v[210:213], v[76:79]
	v_mfma_f32_16x16x32_bf16 v[72:75], v[128:131], v[210:213], v[72:75]
	v_mfma_f32_16x16x32_bf16 v[132:135], v[144:147], v[160:163], v[132:135]
	v_mfma_f32_16x16x32_bf16 v[120:123], v[152:155], v[160:163], v[120:123]
	v_mfma_f32_16x16x32_bf16 v[100:103], v[144:147], v[168:171], v[100:103]
	v_mfma_f32_16x16x32_bf16 v[96:99], v[152:155], v[168:171], v[96:99]
	v_mfma_f32_16x16x32_bf16 v[84:87], v[144:147], v[176:179], v[84:87]
	v_mfma_f32_16x16x32_bf16 v[80:83], v[152:155], v[176:179], v[80:83]
	v_mfma_f32_16x16x32_bf16 v[68:71], v[144:147], v[206:209], v[68:71]
	v_mfma_f32_16x16x32_bf16 v[64:67], v[152:155], v[206:209], v[64:67]
	v_mfma_f32_16x16x32_bf16 v[132:135], v[148:151], v[164:167], v[132:135]
	v_mfma_f32_16x16x32_bf16 v[120:123], v[156:159], v[164:167], v[120:123]
	v_mfma_f32_16x16x32_bf16 v[100:103], v[148:151], v[172:175], v[100:103]
	v_mfma_f32_16x16x32_bf16 v[96:99], v[156:159], v[172:175], v[96:99]
	v_mfma_f32_16x16x32_bf16 v[84:87], v[148:151], v[180:183], v[84:87]
	v_mfma_f32_16x16x32_bf16 v[80:83], v[156:159], v[180:183], v[80:83]
	v_mfma_f32_16x16x32_bf16 v[68:71], v[148:151], v[210:213], v[68:71]
	v_mfma_f32_16x16x32_bf16 v[64:67], v[156:159], v[210:213], v[64:67]
	s_barrier
	s_setprio 0
	s_add_i32 s50, s88, s13
	v_lshl_add_u64 v[196:197], v[196:197], 0, s[30:31]
	s_mov_b32 m0, s50
	ds_read_b128 v[160:163], v202 offset:49152
	ds_read_b128 v[164:167], v202 offset:50176
	ds_read_b128 v[168:171], v202 offset:51200
	ds_read_b128 v[172:175], v202 offset:52224
	ds_read_b128 v[176:179], v202 offset:53248
	ds_read_b128 v[180:183], v202 offset:54272
	ds_read_b128 v[206:209], v202 offset:55296
	ds_read_b128 v[210:213], v202 offset:56320
	global_load_lds_dwordx4 v[196:197], off
	s_add_i32 m0, s50, 0x2000
	s_add_u32 s48, s48, 0x40080
	v_lshl_add_u64 v[196:197], v[214:215], 0, s[30:31]
	s_addc_u32 s49, s49, 0
	s_add_i32 s50, s89, s13
	global_load_lds_dwordx4 v[196:197], off
	v_lshl_add_u64 v[196:197], s[48:49], 0, v[184:185]
	s_mov_b32 m0, s50
	s_nop 0
	global_load_lds_dwordx4 v[196:197], off
	v_lshl_add_u64 v[196:197], s[48:49], 0, v[186:187]
	s_add_i32 m0, s50, 0x2000
	s_nop 0
	global_load_lds_dwordx4 v[196:197], off
	v_lshl_add_u64 v[196:197], v[216:217], 0, s[30:31]
	s_mov_b32 m0, s61
	s_nop 0
	global_load_lds_dwordx4 v[196:197], off
	v_lshl_add_u64 v[196:197], v[218:219], 0, s[30:31]
	s_mov_b32 m0, s62
	s_nop 0
	global_load_lds_dwordx4 v[196:197], off
	s_waitcnt vmcnt(8)
	s_waitcnt lgkmcnt(0)
	s_setprio 1
	s_barrier
	v_mfma_f32_16x16x32_bf16 v[60:63], v[104:107], v[160:163], v[60:63]
	v_mfma_f32_16x16x32_bf16 v[56:59], v[124:127], v[160:163], v[56:59]
	v_mfma_f32_16x16x32_bf16 v[44:47], v[104:107], v[168:171], v[44:47]
	v_mfma_f32_16x16x32_bf16 v[40:43], v[124:127], v[168:171], v[40:43]
	v_mfma_f32_16x16x32_bf16 v[28:31], v[104:107], v[176:179], v[28:31]
	v_mfma_f32_16x16x32_bf16 v[24:27], v[124:127], v[176:179], v[24:27]
	v_mfma_f32_16x16x32_bf16 v[12:15], v[104:107], v[206:209], v[12:15]
	v_mfma_f32_16x16x32_bf16 v[8:11], v[124:127], v[206:209], v[8:11]
	v_mfma_f32_16x16x32_bf16 v[60:63], v[108:111], v[164:167], v[60:63]
	v_mfma_f32_16x16x32_bf16 v[56:59], v[128:131], v[164:167], v[56:59]
	v_mfma_f32_16x16x32_bf16 v[44:47], v[108:111], v[172:175], v[44:47]
	v_mfma_f32_16x16x32_bf16 v[40:43], v[128:131], v[172:175], v[40:43]
	v_mfma_f32_16x16x32_bf16 v[28:31], v[108:111], v[180:183], v[28:31]
	v_mfma_f32_16x16x32_bf16 v[24:27], v[128:131], v[180:183], v[24:27]
	v_mfma_f32_16x16x32_bf16 v[12:15], v[108:111], v[210:213], v[12:15]
	v_mfma_f32_16x16x32_bf16 v[8:11], v[128:131], v[210:213], v[8:11]
	v_mfma_f32_16x16x32_bf16 v[52:55], v[144:147], v[160:163], v[52:55]
	v_mfma_f32_16x16x32_bf16 v[48:51], v[152:155], v[160:163], v[48:51]
	v_mfma_f32_16x16x32_bf16 v[36:39], v[144:147], v[168:171], v[36:39]
	v_mfma_f32_16x16x32_bf16 v[32:35], v[152:155], v[168:171], v[32:35]
	v_mfma_f32_16x16x32_bf16 v[20:23], v[144:147], v[176:179], v[20:23]
	v_mfma_f32_16x16x32_bf16 v[16:19], v[152:155], v[176:179], v[16:19]
	v_mfma_f32_16x16x32_bf16 v[4:7], v[144:147], v[206:209], v[4:7]
	v_mfma_f32_16x16x32_bf16 v[0:3], v[152:155], v[206:209], v[0:3]
	v_mfma_f32_16x16x32_bf16 v[52:55], v[148:151], v[164:167], v[52:55]
	v_mfma_f32_16x16x32_bf16 v[48:51], v[156:159], v[164:167], v[48:51]
	v_mfma_f32_16x16x32_bf16 v[36:39], v[148:151], v[172:175], v[36:39]
	v_mfma_f32_16x16x32_bf16 v[32:35], v[156:159], v[172:175], v[32:35]
	v_mfma_f32_16x16x32_bf16 v[20:23], v[148:151], v[180:183], v[20:23]
	v_mfma_f32_16x16x32_bf16 v[16:19], v[156:159], v[180:183], v[16:19]
	v_mfma_f32_16x16x32_bf16 v[4:7], v[148:151], v[210:213], v[4:7]
	v_mfma_f32_16x16x32_bf16 v[0:3], v[156:159], v[210:213], v[0:3]
	s_barrier
	s_setprio 0
	s_add_i32 s87, s87, 2
	s_add_u32 s46, s46, 0x100
	s_addc_u32 s47, s47, 0
	s_add_u32 s85, s85, 0x100
	s_addc_u32 s86, s86, 0
	s_cmp_gt_u32 s87, 13
	s_cbranch_scc0 .LBB0_504
	s_and_b64 vcc, exec, s[34:35]
	s_cbranch_vccz .LBB0_507
	s_barrier

.LBB0_552:
	ds_read_b128 v[128:131], v173
	ds_read_b128 v[132:135], v173 offset:1024
	ds_read_b128 v[136:139], v173 offset:2048
	ds_read_b128 v[140:143], v173 offset:3072
	ds_read_b128 v[160:163], v179
	ds_read_b128 v[174:177], v179 offset:1024
	ds_read_b128 v[194:197], v179 offset:2048
	ds_read_b128 v[198:201], v179 offset:3072
	s_add_u32 s57, s62, 0xfffc0080
	s_addc_u32 s64, s63, -1
	s_cmp_eq_u32 s55, 12
	s_cselect_b32 s67, s9, s64
	s_cselect_b32 s66, s11, s57
	s_cselect_b32 s65, s13, s23
	s_cselect_b32 s64, s16, s22
	v_lshl_add_u64 v[166:167], s[62:63], 0, v[152:153]
	s_add_i32 m0, s86, 0xc000
	ds_read_b128 v[202:205], v183
	ds_read_b128 v[206:209], v183 offset:1024
	ds_read_b128 v[210:213], v183 offset:2048
	ds_read_b128 v[214:217], v183 offset:3072
	ds_read_b128 v[218:221], v183 offset:4096
	ds_read_b128 v[222:225], v183 offset:5120
	ds_read_b128 v[226:229], v183 offset:6144
	ds_read_b128 v[230:233], v183 offset:7168
	global_load_lds_dwordx4 v[166:167], off
	v_lshl_add_u64 v[166:167], s[62:63], 0, v[154:155]
	s_add_i32 m0, s86, 0xe000
	s_nop 0
	global_load_lds_dwordx4 v[166:167], off
	s_waitcnt vmcnt(8)
	s_waitcnt lgkmcnt(0)
	s_setprio 1
	s_barrier
	v_mfma_f32_16x16x32_bf16 v[124:127], v[128:131], v[202:205], v[124:127]
	v_mfma_f32_16x16x32_bf16 v[120:123], v[136:139], v[202:205], v[120:123]
	v_mfma_f32_16x16x32_bf16 v[108:111], v[128:131], v[210:213], v[108:111]
	v_mfma_f32_16x16x32_bf16 v[104:107], v[136:139], v[210:213], v[104:107]
	v_mfma_f32_16x16x32_bf16 v[92:95], v[128:131], v[218:221], v[92:95]
	v_mfma_f32_16x16x32_bf16 v[88:91], v[136:139], v[218:221], v[88:91]
	v_mfma_f32_16x16x32_bf16 v[76:79], v[128:131], v[226:229], v[76:79]
	v_mfma_f32_16x16x32_bf16 v[72:75], v[136:139], v[226:229], v[72:75]
	v_mfma_f32_16x16x32_bf16 v[124:127], v[132:135], v[206:209], v[124:127]
	v_mfma_f32_16x16x32_bf16 v[120:123], v[140:143], v[206:209], v[120:123]
	v_mfma_f32_16x16x32_bf16 v[108:111], v[132:135], v[214:217], v[108:111]
	v_mfma_f32_16x16x32_bf16 v[104:107], v[140:143], v[214:217], v[104:107]
	v_mfma_f32_16x16x32_bf16 v[92:95], v[132:135], v[222:225], v[92:95]
	v_mfma_f32_16x16x32_bf16 v[88:91], v[140:143], v[222:225], v[88:91]
	v_mfma_f32_16x16x32_bf16 v[76:79], v[132:135], v[230:233], v[76:79]
	v_mfma_f32_16x16x32_bf16 v[72:75], v[140:143], v[230:233], v[72:75]
	v_mfma_f32_16x16x32_bf16 v[116:119], v[160:163], v[202:205], v[116:119]
	v_mfma_f32_16x16x32_bf16 v[112:115], v[194:197], v[202:205], v[112:115]
	v_mfma_f32_16x16x32_bf16 v[100:103], v[160:163], v[210:213], v[100:103]
	v_mfma_f32_16x16x32_bf16 v[96:99], v[194:197], v[210:213], v[96:99]
	v_mfma_f32_16x16x32_bf16 v[84:87], v[160:163], v[218:221], v[84:87]
	v_mfma_f32_16x16x32_bf16 v[80:83], v[194:197], v[218:221], v[80:83]
	v_mfma_f32_16x16x32_bf16 v[68:71], v[160:163], v[226:229], v[68:71]
	v_mfma_f32_16x16x32_bf16 v[64:67], v[194:197], v[226:229], v[64:67]
	v_mfma_f32_16x16x32_bf16 v[116:119], v[174:177], v[206:209], v[116:119]
	v_mfma_f32_16x16x32_bf16 v[112:115], v[198:201], v[206:209], v[112:115]
	v_mfma_f32_16x16x32_bf16 v[100:103], v[174:177], v[214:217], v[100:103]
	v_mfma_f32_16x16x32_bf16 v[96:99], v[198:201], v[214:217], v[96:99]
	v_mfma_f32_16x16x32_bf16 v[84:87], v[174:177], v[222:225], v[84:87]
	v_mfma_f32_16x16x32_bf16 v[80:83], v[198:201], v[222:225], v[80:83]
	v_mfma_f32_16x16x32_bf16 v[68:71], v[174:177], v[230:233], v[68:71]
	v_mfma_f32_16x16x32_bf16 v[64:67], v[198:201], v[230:233], v[64:67]
	s_barrier
	s_setprio 0
	s_add_i32 s57, s0, s85
	v_lshl_add_u64 v[166:167], s[64:65], 0, v[144:145]
	s_mov_b32 m0, s57
	ds_read_b128 v[202:205], v183 offset:16384
	ds_read_b128 v[206:209], v183 offset:17408
	ds_read_b128 v[210:213], v183 offset:18432
	ds_read_b128 v[214:217], v183 offset:19456
	ds_read_b128 v[218:221], v183 offset:20480
	ds_read_b128 v[222:225], v183 offset:21504
	ds_read_b128 v[226:229], v183 offset:22528
	ds_read_b128 v[230:233], v183 offset:23552
	global_load_lds_dwordx4 v[166:167], off
	s_add_i32 m0, s57, 0x2000
	s_add_u32 s68, s64, 0x40000
	v_lshl_add_u64 v[170:171], s[64:65], 0, v[146:147]
	s_addc_u32 s69, s65, 0
	s_add_i32 s57, s1, s85
	global_load_lds_dwordx4 v[170:171], off
	v_lshl_add_u64 v[180:181], s[68:69], 0, v[144:145]
	s_mov_b32 m0, s57
	v_lshl_add_u64 v[184:185], s[66:67], 0, v[146:147]
	global_load_lds_dwordx4 v[180:181], off
	v_lshl_add_u64 v[180:181], s[68:69], 0, v[146:147]
	s_add_i32 m0, s57, 0x2000
	s_nop 0
	global_load_lds_dwordx4 v[180:181], off
	v_lshl_add_u64 v[180:181], s[66:67], 0, v[144:145]
	s_mov_b32 m0, s86
	s_nop 0
	global_load_lds_dwordx4 v[180:181], off
	s_mov_b32 m0, s87
	s_nop 0
	global_load_lds_dwordx4 v[184:185], off
	s_waitcnt vmcnt(8)
	s_waitcnt lgkmcnt(0)
	s_setprio 1
	s_barrier
	v_mfma_f32_16x16x32_bf16 v[60:63], v[128:131], v[202:205], v[60:63]
	v_mfma_f32_16x16x32_bf16 v[56:59], v[136:139], v[202:205], v[56:59]
	v_mfma_f32_16x16x32_bf16 v[44:47], v[128:131], v[210:213], v[44:47]
	v_mfma_f32_16x16x32_bf16 v[40:43], v[136:139], v[210:213], v[40:43]
	v_mfma_f32_16x16x32_bf16 v[28:31], v[128:131], v[218:221], v[28:31]
	v_mfma_f32_16x16x32_bf16 v[24:27], v[136:139], v[218:221], v[24:27]
	v_mfma_f32_16x16x32_bf16 v[12:15], v[128:131], v[226:229], v[12:15]
	v_mfma_f32_16x16x32_bf16 v[8:11], v[136:139], v[226:229], v[8:11]
	v_mfma_f32_16x16x32_bf16 v[60:63], v[132:135], v[206:209], v[60:63]
	v_mfma_f32_16x16x32_bf16 v[56:59], v[140:143], v[206:209], v[56:59]
	v_mfma_f32_16x16x32_bf16 v[44:47], v[132:135], v[214:217], v[44:47]
	v_mfma_f32_16x16x32_bf16 v[40:43], v[140:143], v[214:217], v[40:43]
	v_mfma_f32_16x16x32_bf16 v[28:31], v[132:135], v[222:225], v[28:31]
	v_mfma_f32_16x16x32_bf16 v[24:27], v[140:143], v[222:225], v[24:27]
	v_mfma_f32_16x16x32_bf16 v[12:15], v[132:135], v[230:233], v[12:15]
	v_mfma_f32_16x16x32_bf16 v[8:11], v[140:143], v[230:233], v[8:11]
	v_mfma_f32_16x16x32_bf16 v[52:55], v[160:163], v[202:205], v[52:55]
	v_mfma_f32_16x16x32_bf16 v[48:51], v[194:197], v[202:205], v[48:51]
	v_mfma_f32_16x16x32_bf16 v[36:39], v[160:163], v[210:213], v[36:39]
	v_mfma_f32_16x16x32_bf16 v[32:35], v[194:197], v[210:213], v[32:35]
	v_mfma_f32_16x16x32_bf16 v[20:23], v[160:163], v[218:221], v[20:23]
	v_mfma_f32_16x16x32_bf16 v[16:19], v[194:197], v[218:221], v[16:19]
	v_mfma_f32_16x16x32_bf16 v[4:7], v[160:163], v[226:229], v[4:7]
	v_mfma_f32_16x16x32_bf16 v[0:3], v[194:197], v[226:229], v[0:3]
	v_mfma_f32_16x16x32_bf16 v[52:55], v[174:177], v[206:209], v[52:55]
	v_mfma_f32_16x16x32_bf16 v[48:51], v[198:201], v[206:209], v[48:51]
	v_mfma_f32_16x16x32_bf16 v[36:39], v[174:177], v[214:217], v[36:39]
	v_mfma_f32_16x16x32_bf16 v[32:35], v[198:201], v[214:217], v[32:35]
	v_mfma_f32_16x16x32_bf16 v[20:23], v[174:177], v[222:225], v[20:23]
	v_mfma_f32_16x16x32_bf16 v[16:19], v[198:201], v[222:225], v[16:19]
	v_mfma_f32_16x16x32_bf16 v[4:7], v[174:177], v[230:233], v[4:7]
	v_mfma_f32_16x16x32_bf16 v[0:3], v[198:201], v[230:233], v[0:3]
	s_barrier
	s_setprio 0
	s_add_i32 s57, 0, 0x18000
	s_add_i32 s68, 0, 0x1c000
	v_add_u32_e32 v140, s57, v169
	v_add_u32_e32 v148, s68, v169
	ds_read_b128 v[128:131], v140
	ds_read_b128 v[132:135], v140 offset:1024
	ds_read_b128 v[136:139], v140 offset:2048
	ds_read_b128 v[140:143], v140 offset:3072
	ds_read_b128 v[160:163], v148
	ds_read_b128 v[174:177], v148 offset:1024
	ds_read_b128 v[194:197], v148 offset:2048
	ds_read_b128 v[198:201], v148 offset:3072
	s_add_u32 s66, s66, 0x40000
	s_addc_u32 s67, s67, 0
	s_mov_b32 m0, s88
	v_lshl_add_u64 v[188:189], s[66:67], 0, v[144:145]
	ds_read_b128 v[202:205], v183 offset:32768
	ds_read_b128 v[206:209], v183 offset:33792
	ds_read_b128 v[210:213], v183 offset:34816
	ds_read_b128 v[214:217], v183 offset:35840
	ds_read_b128 v[218:221], v183 offset:36864
	ds_read_b128 v[222:225], v183 offset:37888
	ds_read_b128 v[226:229], v183 offset:38912
	ds_read_b128 v[230:233], v183 offset:39936
	global_load_lds_dwordx4 v[188:189], off
	v_lshl_add_u64 v[188:189], s[66:67], 0, v[146:147]
	s_mov_b32 m0, s89
	s_nop 0
	global_load_lds_dwordx4 v[188:189], off
	s_waitcnt vmcnt(8)
	s_waitcnt lgkmcnt(0)
	s_setprio 1
	s_barrier
	v_mfma_f32_16x16x32_bf16 v[124:127], v[128:131], v[202:205], v[124:127]
	v_mfma_f32_16x16x32_bf16 v[120:123], v[136:139], v[202:205], v[120:123]
	v_mfma_f32_16x16x32_bf16 v[108:111], v[128:131], v[210:213], v[108:111]
	v_mfma_f32_16x16x32_bf16 v[104:107], v[136:139], v[210:213], v[104:107]
	v_mfma_f32_16x16x32_bf16 v[92:95], v[128:131], v[218:221], v[92:95]
	v_mfma_f32_16x16x32_bf16 v[88:91], v[136:139], v[218:221], v[88:91]
	v_mfma_f32_16x16x32_bf16 v[76:79], v[128:131], v[226:229], v[76:79]
	v_mfma_f32_16x16x32_bf16 v[72:75], v[136:139], v[226:229], v[72:75]
	v_mfma_f32_16x16x32_bf16 v[124:127], v[132:135], v[206:209], v[124:127]
	v_mfma_f32_16x16x32_bf16 v[120:123], v[140:143], v[206:209], v[120:123]
	v_mfma_f32_16x16x32_bf16 v[108:111], v[132:135], v[214:217], v[108:111]
	v_mfma_f32_16x16x32_bf16 v[104:107], v[140:143], v[214:217], v[104:107]
	v_mfma_f32_16x16x32_bf16 v[92:95], v[132:135], v[222:225], v[92:95]
	v_mfma_f32_16x16x32_bf16 v[88:91], v[140:143], v[222:225], v[88:91]
	v_mfma_f32_16x16x32_bf16 v[76:79], v[132:135], v[230:233], v[76:79]
	v_mfma_f32_16x16x32_bf16 v[72:75], v[140:143], v[230:233], v[72:75]
	v_mfma_f32_16x16x32_bf16 v[116:119], v[160:163], v[202:205], v[116:119]
	v_mfma_f32_16x16x32_bf16 v[112:115], v[194:197], v[202:205], v[112:115]
	v_mfma_f32_16x16x32_bf16 v[100:103], v[160:163], v[210:213], v[100:103]
	v_mfma_f32_16x16x32_bf16 v[96:99], v[194:197], v[210:213], v[96:99]
	v_mfma_f32_16x16x32_bf16 v[84:87], v[160:163], v[218:221], v[84:87]
	v_mfma_f32_16x16x32_bf16 v[80:83], v[194:197], v[218:221], v[80:83]
	v_mfma_f32_16x16x32_bf16 v[68:71], v[160:163], v[226:229], v[68:71]
	v_mfma_f32_16x16x32_bf16 v[64:67], v[194:197], v[226:229], v[64:67]
	v_mfma_f32_16x16x32_bf16 v[116:119], v[174:177], v[206:209], v[116:119]
	v_mfma_f32_16x16x32_bf16 v[112:115], v[198:201], v[206:209], v[112:115]
	v_mfma_f32_16x16x32_bf16 v[100:103], v[174:177], v[214:217], v[100:103]
	v_mfma_f32_16x16x32_bf16 v[96:99], v[198:201], v[214:217], v[96:99]
	v_mfma_f32_16x16x32_bf16 v[84:87], v[174:177], v[222:225], v[84:87]
	v_mfma_f32_16x16x32_bf16 v[80:83], v[198:201], v[222:225], v[80:83]
	v_mfma_f32_16x16x32_bf16 v[68:71], v[174:177], v[230:233], v[68:71]
	v_mfma_f32_16x16x32_bf16 v[64:67], v[198:201], v[230:233], v[64:67]
	s_barrier
	s_setprio 0
	s_add_i32 s57, s57, s85
	v_lshl_add_u64 v[166:167], v[166:167], 0, s[42:43]
	s_mov_b32 m0, s57
	ds_read_b128 v[202:205], v183 offset:49152
	ds_read_b128 v[206:209], v183 offset:50176
	ds_read_b128 v[210:213], v183 offset:51200
	ds_read_b128 v[214:217], v183 offset:52224
	ds_read_b128 v[218:221], v183 offset:53248
	ds_read_b128 v[222:225], v183 offset:54272
	ds_read_b128 v[226:229], v183 offset:55296
	ds_read_b128 v[230:233], v183 offset:56320
	global_load_lds_dwordx4 v[166:167], off
	s_add_i32 m0, s57, 0x2000
	s_add_u32 s64, s64, 0x40080
	v_lshl_add_u64 v[166:167], v[170:171], 0, s[42:43]
	s_addc_u32 s65, s65, 0
	s_add_i32 s57, s68, s85
	global_load_lds_dwordx4 v[166:167], off
	v_lshl_add_u64 v[166:167], s[64:65], 0, v[144:145]
	s_mov_b32 m0, s57
	s_nop 0
	global_load_lds_dwordx4 v[166:167], off
	v_lshl_add_u64 v[166:167], s[64:65], 0, v[146:147]
	s_add_i32 m0, s57, 0x2000
	s_nop 0
	global_load_lds_dwordx4 v[166:167], off
	v_lshl_add_u64 v[166:167], v[180:181], 0, s[42:43]
	s_mov_b32 m0, s94
	s_nop 0
	global_load_lds_dwordx4 v[166:167], off
	v_lshl_add_u64 v[166:167], v[184:185], 0, s[42:43]
	s_mov_b32 m0, s95
	s_nop 0
	global_load_lds_dwordx4 v[166:167], off
	s_waitcnt vmcnt(8)
	s_waitcnt lgkmcnt(0)
	s_setprio 1
	s_barrier
	v_mfma_f32_16x16x32_bf16 v[60:63], v[128:131], v[202:205], v[60:63]
	v_mfma_f32_16x16x32_bf16 v[56:59], v[136:139], v[202:205], v[56:59]
	v_mfma_f32_16x16x32_bf16 v[44:47], v[128:131], v[210:213], v[44:47]
	v_mfma_f32_16x16x32_bf16 v[40:43], v[136:139], v[210:213], v[40:43]
	v_mfma_f32_16x16x32_bf16 v[28:31], v[128:131], v[218:221], v[28:31]
	v_mfma_f32_16x16x32_bf16 v[24:27], v[136:139], v[218:221], v[24:27]
	v_mfma_f32_16x16x32_bf16 v[12:15], v[128:131], v[226:229], v[12:15]
	v_mfma_f32_16x16x32_bf16 v[8:11], v[136:139], v[226:229], v[8:11]
	v_mfma_f32_16x16x32_bf16 v[60:63], v[132:135], v[206:209], v[60:63]
	v_mfma_f32_16x16x32_bf16 v[56:59], v[140:143], v[206:209], v[56:59]
	v_mfma_f32_16x16x32_bf16 v[44:47], v[132:135], v[214:217], v[44:47]
	v_mfma_f32_16x16x32_bf16 v[40:43], v[140:143], v[214:217], v[40:43]
	v_mfma_f32_16x16x32_bf16 v[28:31], v[132:135], v[222:225], v[28:31]
	v_mfma_f32_16x16x32_bf16 v[24:27], v[140:143], v[222:225], v[24:27]
	v_mfma_f32_16x16x32_bf16 v[12:15], v[132:135], v[230:233], v[12:15]
	v_mfma_f32_16x16x32_bf16 v[8:11], v[140:143], v[230:233], v[8:11]
	v_mfma_f32_16x16x32_bf16 v[52:55], v[160:163], v[202:205], v[52:55]
	v_mfma_f32_16x16x32_bf16 v[48:51], v[194:197], v[202:205], v[48:51]
	v_mfma_f32_16x16x32_bf16 v[36:39], v[160:163], v[210:213], v[36:39]
	v_mfma_f32_16x16x32_bf16 v[32:35], v[194:197], v[210:213], v[32:35]
	v_mfma_f32_16x16x32_bf16 v[20:23], v[160:163], v[218:221], v[20:23]
	v_mfma_f32_16x16x32_bf16 v[16:19], v[194:197], v[218:221], v[16:19]
	v_mfma_f32_16x16x32_bf16 v[4:7], v[160:163], v[226:229], v[4:7]
	v_mfma_f32_16x16x32_bf16 v[0:3], v[194:197], v[226:229], v[0:3]
	v_mfma_f32_16x16x32_bf16 v[52:55], v[174:177], v[206:209], v[52:55]
	v_mfma_f32_16x16x32_bf16 v[48:51], v[198:201], v[206:209], v[48:51]
	v_mfma_f32_16x16x32_bf16 v[36:39], v[174:177], v[214:217], v[36:39]
	v_mfma_f32_16x16x32_bf16 v[32:35], v[198:201], v[214:217], v[32:35]
	v_mfma_f32_16x16x32_bf16 v[20:23], v[174:177], v[222:225], v[20:23]
	v_mfma_f32_16x16x32_bf16 v[16:19], v[198:201], v[222:225], v[16:19]
	v_mfma_f32_16x16x32_bf16 v[4:7], v[174:177], v[230:233], v[4:7]
	v_mfma_f32_16x16x32_bf16 v[0:3], v[198:201], v[230:233], v[0:3]
	s_barrier
	s_setprio 0
	s_add_i32 s55, s55, 2
	s_add_u32 s62, s62, 0x100
	s_addc_u32 s63, s63, 0
	s_add_u32 s22, s22, 0x100
	s_addc_u32 s23, s23, 0
	s_cmp_gt_u32 s55, 13
	s_cbranch_scc0 .LBB0_552
	s_and_b64 vcc, exec, s[44:45]
	s_cbranch_vccz .LBB0_555
	s_barrier

.Lkv_nopf:
	s_barrier
	v_mfma_f32_16x16x32_bf16 v[124:127], v[150:153], v[182:185], v[124:127]
	v_mfma_f32_16x16x32_bf16 v[120:123], v[158:161], v[182:185], v[120:123]
	v_mfma_f32_16x16x32_bf16 v[108:111], v[150:153], v[190:193], v[108:111]
	v_mfma_f32_16x16x32_bf16 v[104:107], v[158:161], v[190:193], v[104:107]
	v_mfma_f32_16x16x32_bf16 v[92:95], v[150:153], v[198:201], v[92:95]
	v_mfma_f32_16x16x32_bf16 v[88:91], v[158:161], v[198:201], v[88:91]
	v_mfma_f32_16x16x32_bf16 v[76:79], v[150:153], v[206:209], v[76:79]
	v_mfma_f32_16x16x32_bf16 v[72:75], v[158:161], v[206:209], v[72:75]
	v_mfma_f32_16x16x32_bf16 v[124:127], v[154:157], v[186:189], v[124:127]
	v_mfma_f32_16x16x32_bf16 v[120:123], v[162:165], v[186:189], v[120:123]
	v_mfma_f32_16x16x32_bf16 v[108:111], v[154:157], v[194:197], v[108:111]
	v_mfma_f32_16x16x32_bf16 v[104:107], v[162:165], v[194:197], v[104:107]
	v_mfma_f32_16x16x32_bf16 v[92:95], v[154:157], v[202:205], v[92:95]
	v_mfma_f32_16x16x32_bf16 v[88:91], v[162:165], v[202:205], v[88:91]
	v_mfma_f32_16x16x32_bf16 v[76:79], v[154:157], v[210:213], v[76:79]
	v_mfma_f32_16x16x32_bf16 v[72:75], v[162:165], v[210:213], v[72:75]
	v_mfma_f32_16x16x32_bf16 v[116:119], v[166:169], v[182:185], v[116:119]
	v_mfma_f32_16x16x32_bf16 v[112:115], v[174:177], v[182:185], v[112:115]
	v_mfma_f32_16x16x32_bf16 v[100:103], v[166:169], v[190:193], v[100:103]
	v_mfma_f32_16x16x32_bf16 v[96:99], v[174:177], v[190:193], v[96:99]
	v_mfma_f32_16x16x32_bf16 v[84:87], v[166:169], v[198:201], v[84:87]
	v_mfma_f32_16x16x32_bf16 v[80:83], v[174:177], v[198:201], v[80:83]
	v_mfma_f32_16x16x32_bf16 v[68:71], v[166:169], v[206:209], v[68:71]
	v_mfma_f32_16x16x32_bf16 v[64:67], v[174:177], v[206:209], v[64:67]
	v_mfma_f32_16x16x32_bf16 v[116:119], v[170:173], v[186:189], v[116:119]
	v_mfma_f32_16x16x32_bf16 v[112:115], v[178:181], v[186:189], v[112:115]
	v_mfma_f32_16x16x32_bf16 v[100:103], v[170:173], v[194:197], v[100:103]
	v_mfma_f32_16x16x32_bf16 v[96:99], v[178:181], v[194:197], v[96:99]
	v_mfma_f32_16x16x32_bf16 v[84:87], v[170:173], v[202:205], v[84:87]
	v_mfma_f32_16x16x32_bf16 v[80:83], v[178:181], v[202:205], v[80:83]
	v_mfma_f32_16x16x32_bf16 v[68:71], v[170:173], v[210:213], v[68:71]
	v_mfma_f32_16x16x32_bf16 v[64:67], v[178:181], v[210:213], v[64:67]
	s_barrier
	s_setprio 0
	s_mov_b32 m0, s93
	v_lshl_add_u64 v[138:139], s[52:53], 0, v[130:131]
	ds_read_b128 v[182:185], v146 offset:16384
	ds_read_b128 v[186:189], v146 offset:17408
	ds_read_b128 v[190:193], v146 offset:18432
	ds_read_b128 v[194:197], v146 offset:19456
	ds_read_b128 v[198:201], v146 offset:20480
	ds_read_b128 v[202:205], v146 offset:21504
	ds_read_b128 v[206:209], v146 offset:22528
	ds_read_b128 v[210:213], v146 offset:23552
	global_load_lds_dwordx4 v[138:139], off
	v_lshl_add_u64 v[214:215], s[52:53], 0, v[128:129]
	s_mov_b32 m0, s90
	v_lshl_add_u64 v[216:217], s[54:55], 0, v[130:131]
	global_load_lds_dwordx4 v[214:215], off
	s_mov_b32 m0, s92
	v_lshl_add_u64 v[218:219], s[50:51], 0, v[128:129]
	global_load_lds_dwordx4 v[216:217], off
	v_lshl_add_u64 v[216:217], s[54:55], 0, v[128:129]
	s_mov_b32 m0, s91
	s_nop 0
	global_load_lds_dwordx4 v[216:217], off
	v_lshl_add_u64 v[216:217], s[50:51], 0, v[130:131]
	s_mov_b32 m0, s61
	s_nop 0
	global_load_lds_dwordx4 v[216:217], off
	s_mov_b32 m0, s62
	s_nop 0
	global_load_lds_dwordx4 v[218:219], off
	s_waitcnt vmcnt(8)
	s_waitcnt lgkmcnt(0)
	s_setprio 1
	s_barrier
	v_mfma_f32_16x16x32_bf16 v[60:63], v[150:153], v[182:185], v[60:63]
	v_mfma_f32_16x16x32_bf16 v[56:59], v[158:161], v[182:185], v[56:59]
	v_mfma_f32_16x16x32_bf16 v[44:47], v[150:153], v[190:193], v[44:47]
	v_mfma_f32_16x16x32_bf16 v[40:43], v[158:161], v[190:193], v[40:43]
	v_mfma_f32_16x16x32_bf16 v[28:31], v[150:153], v[198:201], v[28:31]
	v_mfma_f32_16x16x32_bf16 v[24:27], v[158:161], v[198:201], v[24:27]
	v_mfma_f32_16x16x32_bf16 v[12:15], v[150:153], v[206:209], v[12:15]
	v_mfma_f32_16x16x32_bf16 v[8:11], v[158:161], v[206:209], v[8:11]
	v_mfma_f32_16x16x32_bf16 v[60:63], v[154:157], v[186:189], v[60:63]
	v_mfma_f32_16x16x32_bf16 v[56:59], v[162:165], v[186:189], v[56:59]
	v_mfma_f32_16x16x32_bf16 v[44:47], v[154:157], v[194:197], v[44:47]
	v_mfma_f32_16x16x32_bf16 v[40:43], v[162:165], v[194:197], v[40:43]
	v_mfma_f32_16x16x32_bf16 v[28:31], v[154:157], v[202:205], v[28:31]
	v_mfma_f32_16x16x32_bf16 v[24:27], v[162:165], v[202:205], v[24:27]
	v_mfma_f32_16x16x32_bf16 v[12:15], v[154:157], v[210:213], v[12:15]
	v_mfma_f32_16x16x32_bf16 v[8:11], v[162:165], v[210:213], v[8:11]
	v_mfma_f32_16x16x32_bf16 v[52:55], v[166:169], v[182:185], v[52:55]
	v_mfma_f32_16x16x32_bf16 v[48:51], v[174:177], v[182:185], v[48:51]
	v_mfma_f32_16x16x32_bf16 v[36:39], v[166:169], v[190:193], v[36:39]
	v_mfma_f32_16x16x32_bf16 v[32:35], v[174:177], v[190:193], v[32:35]
	v_mfma_f32_16x16x32_bf16 v[20:23], v[166:169], v[198:201], v[20:23]
	v_mfma_f32_16x16x32_bf16 v[16:19], v[174:177], v[198:201], v[16:19]
	v_mfma_f32_16x16x32_bf16 v[4:7], v[166:169], v[206:209], v[4:7]
	v_mfma_f32_16x16x32_bf16 v[0:3], v[174:177], v[206:209], v[0:3]
	v_mfma_f32_16x16x32_bf16 v[52:55], v[170:173], v[186:189], v[52:55]
	v_mfma_f32_16x16x32_bf16 v[48:51], v[178:181], v[186:189], v[48:51]
	v_mfma_f32_16x16x32_bf16 v[36:39], v[170:173], v[194:197], v[36:39]
	v_mfma_f32_16x16x32_bf16 v[32:35], v[178:181], v[194:197], v[32:35]
	v_mfma_f32_16x16x32_bf16 v[20:23], v[170:173], v[202:205], v[20:23]
	v_mfma_f32_16x16x32_bf16 v[16:19], v[178:181], v[202:205], v[16:19]
	v_mfma_f32_16x16x32_bf16 v[4:7], v[170:173], v[210:213], v[4:7]
	v_mfma_f32_16x16x32_bf16 v[0:3], v[178:181], v[210:213], v[0:3]
	s_barrier
	s_setprio 0
	v_add_u32_e32 v132, s89, v143
	ds_read_b128 v[150:153], v132
	ds_read_b128 v[154:157], v132 offset:1024
	ds_read_b128 v[158:161], v132 offset:2048
	ds_read_b128 v[162:165], v132 offset:3072
	v_add_u32_e32 v132, s88, v143
	ds_read_b128 v[166:169], v132
	ds_read_b128 v[170:173], v132 offset:1024
	ds_read_b128 v[174:177], v132 offset:2048
	ds_read_b128 v[178:181], v132 offset:3072
	s_mov_b32 m0, s63
	v_lshl_add_u64 v[220:221], s[48:49], 0, v[130:131]
	ds_read_b128 v[182:185], v146 offset:32768
	ds_read_b128 v[186:189], v146 offset:33792
	ds_read_b128 v[190:193], v146 offset:34816
	ds_read_b128 v[194:197], v146 offset:35840
	ds_read_b128 v[198:201], v146 offset:36864
	ds_read_b128 v[202:205], v146 offset:37888
	ds_read_b128 v[206:209], v146 offset:38912
	ds_read_b128 v[210:213], v146 offset:39936
	global_load_lds_dwordx4 v[220:221], off
	v_lshl_add_u64 v[220:221], s[48:49], 0, v[128:129]
	s_mov_b32 m0, s64
	s_nop 0
	global_load_lds_dwordx4 v[220:221], off
	s_waitcnt vmcnt(8)
	s_waitcnt lgkmcnt(0)
	s_setprio 1
	s_barrier
	v_mfma_f32_16x16x32_bf16 v[124:127], v[150:153], v[182:185], v[124:127]
	v_mfma_f32_16x16x32_bf16 v[120:123], v[158:161], v[182:185], v[120:123]
	v_mfma_f32_16x16x32_bf16 v[108:111], v[150:153], v[190:193], v[108:111]
	v_mfma_f32_16x16x32_bf16 v[104:107], v[158:161], v[190:193], v[104:107]
	v_mfma_f32_16x16x32_bf16 v[92:95], v[150:153], v[198:201], v[92:95]
	v_mfma_f32_16x16x32_bf16 v[88:91], v[158:161], v[198:201], v[88:91]
	v_mfma_f32_16x16x32_bf16 v[76:79], v[150:153], v[206:209], v[76:79]
	v_mfma_f32_16x16x32_bf16 v[72:75], v[158:161], v[206:209], v[72:75]
	v_mfma_f32_16x16x32_bf16 v[124:127], v[154:157], v[186:189], v[124:127]
	v_mfma_f32_16x16x32_bf16 v[120:123], v[162:165], v[186:189], v[120:123]
	v_mfma_f32_16x16x32_bf16 v[108:111], v[154:157], v[194:197], v[108:111]
	v_mfma_f32_16x16x32_bf16 v[104:107], v[162:165], v[194:197], v[104:107]
	v_mfma_f32_16x16x32_bf16 v[92:95], v[154:157], v[202:205], v[92:95]
	v_mfma_f32_16x16x32_bf16 v[88:91], v[162:165], v[202:205], v[88:91]
	v_mfma_f32_16x16x32_bf16 v[76:79], v[154:157], v[210:213], v[76:79]
	v_mfma_f32_16x16x32_bf16 v[72:75], v[162:165], v[210:213], v[72:75]
	v_mfma_f32_16x16x32_bf16 v[116:119], v[166:169], v[182:185], v[116:119]
	v_mfma_f32_16x16x32_bf16 v[112:115], v[174:177], v[182:185], v[112:115]
	v_mfma_f32_16x16x32_bf16 v[100:103], v[166:169], v[190:193], v[100:103]
	v_mfma_f32_16x16x32_bf16 v[96:99], v[174:177], v[190:193], v[96:99]
	v_mfma_f32_16x16x32_bf16 v[84:87], v[166:169], v[198:201], v[84:87]
	v_mfma_f32_16x16x32_bf16 v[80:83], v[174:177], v[198:201], v[80:83]
	v_mfma_f32_16x16x32_bf16 v[68:71], v[166:169], v[206:209], v[68:71]
	v_mfma_f32_16x16x32_bf16 v[64:67], v[174:177], v[206:209], v[64:67]
	v_mfma_f32_16x16x32_bf16 v[116:119], v[170:173], v[186:189], v[116:119]
	v_mfma_f32_16x16x32_bf16 v[112:115], v[178:181], v[186:189], v[112:115]
	v_mfma_f32_16x16x32_bf16 v[100:103], v[170:173], v[194:197], v[100:103]
	v_mfma_f32_16x16x32_bf16 v[96:99], v[178:181], v[194:197], v[96:99]
	v_mfma_f32_16x16x32_bf16 v[84:87], v[170:173], v[202:205], v[84:87]
	v_mfma_f32_16x16x32_bf16 v[80:83], v[178:181], v[202:205], v[80:83]
	v_mfma_f32_16x16x32_bf16 v[68:71], v[170:173], v[210:213], v[68:71]
	v_mfma_f32_16x16x32_bf16 v[64:67], v[178:181], v[210:213], v[64:67]
	s_barrier
	s_setprio 0
	s_mov_b32 m0, s87
	v_lshl_add_u64 v[138:139], v[138:139], 0, s[16:17]
	ds_read_b128 v[182:185], v146 offset:49152
	ds_read_b128 v[186:189], v146 offset:50176
	ds_read_b128 v[190:193], v146 offset:51200
	ds_read_b128 v[194:197], v146 offset:52224
	ds_read_b128 v[198:201], v146 offset:53248
	ds_read_b128 v[202:205], v146 offset:54272
	ds_read_b128 v[206:209], v146 offset:55296
	ds_read_b128 v[210:213], v146 offset:56320
	global_load_lds_dwordx4 v[138:139], off
	v_lshl_add_u64 v[138:139], v[214:215], 0, s[16:17]
	s_mov_b32 m0, s85
	s_nop 0
	global_load_lds_dwordx4 v[138:139], off
	v_lshl_add_u64 v[138:139], s[46:47], 0, v[130:131]
	s_mov_b32 m0, s86
	s_nop 0
	global_load_lds_dwordx4 v[138:139], off
	v_lshl_add_u64 v[138:139], s[46:47], 0, v[128:129]
	s_mov_b32 m0, s84
	s_nop 0
	global_load_lds_dwordx4 v[138:139], off
	v_lshl_add_u64 v[138:139], v[216:217], 0, s[16:17]
	s_mov_b32 m0, s70
	s_nop 0
	global_load_lds_dwordx4 v[138:139], off
	v_lshl_add_u64 v[138:139], v[218:219], 0, s[16:17]
	s_mov_b32 m0, s71
	s_nop 0
	global_load_lds_dwordx4 v[138:139], off
	s_waitcnt vmcnt(8)
	s_waitcnt lgkmcnt(0)
	s_setprio 1
	s_barrier
	v_mfma_f32_16x16x32_bf16 v[60:63], v[150:153], v[182:185], v[60:63]
	v_mfma_f32_16x16x32_bf16 v[56:59], v[158:161], v[182:185], v[56:59]
	v_mfma_f32_16x16x32_bf16 v[44:47], v[150:153], v[190:193], v[44:47]
	v_mfma_f32_16x16x32_bf16 v[40:43], v[158:161], v[190:193], v[40:43]
	v_mfma_f32_16x16x32_bf16 v[28:31], v[150:153], v[198:201], v[28:31]
	v_mfma_f32_16x16x32_bf16 v[24:27], v[158:161], v[198:201], v[24:27]
	v_mfma_f32_16x16x32_bf16 v[12:15], v[150:153], v[206:209], v[12:15]
	v_mfma_f32_16x16x32_bf16 v[8:11], v[158:161], v[206:209], v[8:11]
	v_mfma_f32_16x16x32_bf16 v[60:63], v[154:157], v[186:189], v[60:63]
	v_mfma_f32_16x16x32_bf16 v[56:59], v[162:165], v[186:189], v[56:59]
	v_mfma_f32_16x16x32_bf16 v[44:47], v[154:157], v[194:197], v[44:47]
	v_mfma_f32_16x16x32_bf16 v[40:43], v[162:165], v[194:197], v[40:43]
	v_mfma_f32_16x16x32_bf16 v[28:31], v[154:157], v[202:205], v[28:31]
	v_mfma_f32_16x16x32_bf16 v[24:27], v[162:165], v[202:205], v[24:27]
	v_mfma_f32_16x16x32_bf16 v[12:15], v[154:157], v[210:213], v[12:15]
	v_mfma_f32_16x16x32_bf16 v[8:11], v[162:165], v[210:213], v[8:11]
	v_mfma_f32_16x16x32_bf16 v[52:55], v[166:169], v[182:185], v[52:55]
	v_mfma_f32_16x16x32_bf16 v[48:51], v[174:177], v[182:185], v[48:51]
	v_mfma_f32_16x16x32_bf16 v[36:39], v[166:169], v[190:193], v[36:39]
	v_mfma_f32_16x16x32_bf16 v[32:35], v[174:177], v[190:193], v[32:35]
	v_mfma_f32_16x16x32_bf16 v[20:23], v[166:169], v[198:201], v[20:23]
	v_mfma_f32_16x16x32_bf16 v[16:19], v[174:177], v[198:201], v[16:19]
	v_mfma_f32_16x16x32_bf16 v[4:7], v[166:169], v[206:209], v[4:7]
	v_mfma_f32_16x16x32_bf16 v[0:3], v[174:177], v[206:209], v[0:3]
	v_mfma_f32_16x16x32_bf16 v[52:55], v[170:173], v[186:189], v[52:55]
	v_mfma_f32_16x16x32_bf16 v[48:51], v[178:181], v[186:189], v[48:51]
	v_mfma_f32_16x16x32_bf16 v[36:39], v[170:173], v[194:197], v[36:39]
	v_mfma_f32_16x16x32_bf16 v[32:35], v[178:181], v[194:197], v[32:35]
	v_mfma_f32_16x16x32_bf16 v[20:23], v[170:173], v[202:205], v[20:23]
	v_mfma_f32_16x16x32_bf16 v[16:19], v[178:181], v[202:205], v[16:19]
	v_mfma_f32_16x16x32_bf16 v[4:7], v[170:173], v[210:213], v[4:7]
	v_mfma_f32_16x16x32_bf16 v[0:3], v[178:181], v[210:213], v[0:3]
	s_barrier
	s_setprio 0
	s_andn2_b64 vcc, exec, s[44:45]
	s_mov_b64 s[46:47], -1
	s_mov_b64 s[44:45], 0
	s_mov_b64 s[48:49], 0x100
	s_cbranch_vccz .LBB0_744
	s_and_b64 vcc, exec, s[20:21]
	s_cbranch_vccz .LBB0_747
	s_barrier

.LBB0_771:
	ds_read_b128 v[84:87], v208
	ds_read_b128 v[100:103], v208 offset:1024
	ds_read_b128 v[120:123], v208 offset:2048
	ds_read_b128 v[140:143], v208 offset:3072
	ds_read_b128 v[144:147], v209
	ds_read_b128 v[148:151], v209 offset:1024
	ds_read_b128 v[152:155], v209 offset:2048
	ds_read_b128 v[170:173], v209 offset:3072
	s_add_u32 s6, s8, 0x100
	s_addc_u32 s7, s9, 0
	s_cmp_eq_u32 s83, 2
	s_cselect_b32 s41, s35, s7
	s_cselect_b32 s40, s34, s6
	s_cselect_b32 s39, s37, s82
	s_cselect_b32 s38, s36, s81
	v_lshl_add_u64 v[214:215], s[8:9], 0, v[162:163]
	s_add_i32 m0, s42, 0xc000
	ds_read_b128 v[174:177], v210
	ds_read_b128 v[178:181], v210 offset:1024
	ds_read_b128 v[182:185], v210 offset:2048
	ds_read_b128 v[186:189], v210 offset:3072
	ds_read_b128 v[190:193], v210 offset:4096
	ds_read_b128 v[194:197], v210 offset:5120
	ds_read_b128 v[198:201], v210 offset:6144
	ds_read_b128 v[202:205], v210 offset:7168
	global_load_lds_dwordx4 v[214:215], off
	v_lshl_add_u64 v[214:215], s[8:9], 0, v[164:165]
	s_add_i32 m0, s42, 0xe000
	s_nop 0
	global_load_lds_dwordx4 v[214:215], off
	s_waitcnt vmcnt(8)
	s_waitcnt lgkmcnt(0)
	s_setprio 1
	s_barrier
	v_mfma_f32_16x16x32_bf16 v[136:139], v[84:87], v[174:177], v[136:139]
	v_mfma_f32_16x16x32_bf16 v[132:135], v[120:123], v[174:177], v[132:135]
	v_mfma_f32_16x16x32_bf16 v[116:119], v[84:87], v[182:185], v[116:119]
	v_mfma_f32_16x16x32_bf16 v[112:115], v[120:123], v[182:185], v[112:115]
	v_mfma_f32_16x16x32_bf16 v[96:99], v[84:87], v[190:193], v[96:99]
	v_mfma_f32_16x16x32_bf16 v[92:95], v[120:123], v[190:193], v[92:95]
	v_mfma_f32_16x16x32_bf16 v[76:79], v[84:87], v[198:201], v[76:79]
	v_mfma_f32_16x16x32_bf16 v[72:75], v[120:123], v[198:201], v[72:75]
	v_mfma_f32_16x16x32_bf16 v[136:139], v[100:103], v[178:181], v[136:139]
	v_mfma_f32_16x16x32_bf16 v[132:135], v[140:143], v[178:181], v[132:135]
	v_mfma_f32_16x16x32_bf16 v[116:119], v[100:103], v[186:189], v[116:119]
	v_mfma_f32_16x16x32_bf16 v[112:115], v[140:143], v[186:189], v[112:115]
	v_mfma_f32_16x16x32_bf16 v[96:99], v[100:103], v[194:197], v[96:99]
	v_mfma_f32_16x16x32_bf16 v[92:95], v[140:143], v[194:197], v[92:95]
	v_mfma_f32_16x16x32_bf16 v[76:79], v[100:103], v[202:205], v[76:79]
	v_mfma_f32_16x16x32_bf16 v[72:75], v[140:143], v[202:205], v[72:75]
	v_mfma_f32_16x16x32_bf16 v[128:131], v[144:147], v[174:177], v[128:131]
	v_mfma_f32_16x16x32_bf16 v[124:127], v[152:155], v[174:177], v[124:127]
	v_mfma_f32_16x16x32_bf16 v[108:111], v[144:147], v[182:185], v[108:111]
	v_mfma_f32_16x16x32_bf16 v[104:107], v[152:155], v[182:185], v[104:107]
	v_mfma_f32_16x16x32_bf16 v[88:91], v[144:147], v[190:193], v[88:91]
	v_mfma_f32_16x16x32_bf16 v[80:83], v[152:155], v[190:193], v[80:83]
	v_mfma_f32_16x16x32_bf16 v[68:71], v[144:147], v[198:201], v[68:71]
	v_mfma_f32_16x16x32_bf16 v[64:67], v[152:155], v[198:201], v[64:67]
	v_mfma_f32_16x16x32_bf16 v[128:131], v[148:151], v[178:181], v[128:131]
	v_mfma_f32_16x16x32_bf16 v[124:127], v[170:173], v[178:181], v[124:127]
	v_mfma_f32_16x16x32_bf16 v[108:111], v[148:151], v[186:189], v[108:111]
	v_mfma_f32_16x16x32_bf16 v[104:107], v[170:173], v[186:189], v[104:107]
	v_mfma_f32_16x16x32_bf16 v[88:91], v[148:151], v[194:197], v[88:91]
	v_mfma_f32_16x16x32_bf16 v[80:83], v[170:173], v[194:197], v[80:83]
	v_mfma_f32_16x16x32_bf16 v[68:71], v[148:151], v[202:205], v[68:71]
	v_mfma_f32_16x16x32_bf16 v[64:67], v[170:173], v[202:205], v[64:67]
	s_barrier
	s_setprio 0
	s_add_i32 s8, s61, s3
	v_lshl_add_u64 v[214:215], s[38:39], 0, v[156:157]
	s_mov_b32 m0, s8
	ds_read_b128 v[174:177], v210 offset:16384
	ds_read_b128 v[178:181], v210 offset:17408
	ds_read_b128 v[182:185], v210 offset:18432
	ds_read_b128 v[186:189], v210 offset:19456
	ds_read_b128 v[190:193], v210 offset:20480
	ds_read_b128 v[194:197], v210 offset:21504
	ds_read_b128 v[198:201], v210 offset:22528
	ds_read_b128 v[202:205], v210 offset:23552
	global_load_lds_dwordx4 v[214:215], off
	s_add_i32 m0, s8, 0x2000
	s_add_u32 s8, s38, 0x18000
	v_lshl_add_u64 v[216:217], s[38:39], 0, v[158:159]
	s_addc_u32 s9, s39, 0
	s_add_i32 s84, s62, s3
	global_load_lds_dwordx4 v[216:217], off
	v_lshl_add_u64 v[218:219], s[8:9], 0, v[156:157]
	s_mov_b32 m0, s84
	v_lshl_add_u64 v[220:221], s[40:41], 0, v[158:159]
	global_load_lds_dwordx4 v[218:219], off
	v_lshl_add_u64 v[218:219], s[8:9], 0, v[158:159]
	s_add_i32 m0, s84, 0x2000
	s_nop 0
	global_load_lds_dwordx4 v[218:219], off
	v_lshl_add_u64 v[218:219], s[40:41], 0, v[156:157]
	s_mov_b32 m0, s42
	s_nop 0
	global_load_lds_dwordx4 v[218:219], off
	s_mov_b32 m0, s43
	s_nop 0
	global_load_lds_dwordx4 v[220:221], off
	s_waitcnt vmcnt(8)
	s_waitcnt lgkmcnt(0)
	s_setprio 1
	s_barrier
	v_mfma_f32_16x16x32_bf16 v[60:63], v[84:87], v[174:177], v[60:63]
	v_mfma_f32_16x16x32_bf16 v[56:59], v[120:123], v[174:177], v[56:59]
	v_mfma_f32_16x16x32_bf16 v[44:47], v[84:87], v[182:185], v[44:47]
	v_mfma_f32_16x16x32_bf16 v[40:43], v[120:123], v[182:185], v[40:43]
	v_mfma_f32_16x16x32_bf16 v[28:31], v[84:87], v[190:193], v[28:31]
	v_mfma_f32_16x16x32_bf16 v[24:27], v[120:123], v[190:193], v[24:27]
	v_mfma_f32_16x16x32_bf16 v[12:15], v[84:87], v[198:201], v[12:15]
	v_mfma_f32_16x16x32_bf16 v[8:11], v[120:123], v[198:201], v[8:11]
	v_mfma_f32_16x16x32_bf16 v[60:63], v[100:103], v[178:181], v[60:63]
	v_mfma_f32_16x16x32_bf16 v[56:59], v[140:143], v[178:181], v[56:59]
	v_mfma_f32_16x16x32_bf16 v[44:47], v[100:103], v[186:189], v[44:47]
	v_mfma_f32_16x16x32_bf16 v[40:43], v[140:143], v[186:189], v[40:43]
	v_mfma_f32_16x16x32_bf16 v[28:31], v[100:103], v[194:197], v[28:31]
	v_mfma_f32_16x16x32_bf16 v[24:27], v[140:143], v[194:197], v[24:27]
	v_mfma_f32_16x16x32_bf16 v[12:15], v[100:103], v[202:205], v[12:15]
	v_mfma_f32_16x16x32_bf16 v[8:11], v[140:143], v[202:205], v[8:11]
	v_mfma_f32_16x16x32_bf16 v[52:55], v[144:147], v[174:177], v[52:55]
	v_mfma_f32_16x16x32_bf16 v[48:51], v[152:155], v[174:177], v[48:51]
	v_mfma_f32_16x16x32_bf16 v[36:39], v[144:147], v[182:185], v[36:39]
	v_mfma_f32_16x16x32_bf16 v[32:35], v[152:155], v[182:185], v[32:35]
	v_mfma_f32_16x16x32_bf16 v[20:23], v[144:147], v[190:193], v[20:23]
	v_mfma_f32_16x16x32_bf16 v[16:19], v[152:155], v[190:193], v[16:19]
	v_mfma_f32_16x16x32_bf16 v[4:7], v[144:147], v[198:201], v[4:7]
	v_mfma_f32_16x16x32_bf16 v[0:3], v[152:155], v[198:201], v[0:3]
	v_mfma_f32_16x16x32_bf16 v[52:55], v[148:151], v[178:181], v[52:55]
	v_mfma_f32_16x16x32_bf16 v[48:51], v[170:173], v[178:181], v[48:51]
	v_mfma_f32_16x16x32_bf16 v[36:39], v[148:151], v[186:189], v[36:39]
	v_mfma_f32_16x16x32_bf16 v[32:35], v[170:173], v[186:189], v[32:35]
	v_mfma_f32_16x16x32_bf16 v[20:23], v[148:151], v[194:197], v[20:23]
	v_mfma_f32_16x16x32_bf16 v[16:19], v[170:173], v[194:197], v[16:19]
	v_mfma_f32_16x16x32_bf16 v[4:7], v[148:151], v[202:205], v[4:7]
	v_mfma_f32_16x16x32_bf16 v[0:3], v[170:173], v[202:205], v[0:3]
	s_barrier
	s_setprio 0
	s_add_i32 s84, 0, 0x18000
	s_add_i32 s85, 0, 0x1c000
	v_add_u32_e32 v140, s84, v207
	v_add_u32_e32 v160, s85, v207
	ds_read_b128 v[84:87], v140
	ds_read_b128 v[100:103], v140 offset:1024
	ds_read_b128 v[120:123], v140 offset:2048
	ds_read_b128 v[140:143], v140 offset:3072
	ds_read_b128 v[144:147], v160
	ds_read_b128 v[148:151], v160 offset:1024
	ds_read_b128 v[152:155], v160 offset:2048
	ds_read_b128 v[170:173], v160 offset:3072
	s_add_u32 s8, s40, 0x18000
	s_addc_u32 s9, s41, 0
	s_mov_b32 m0, s44
	v_lshl_add_u64 v[222:223], s[8:9], 0, v[156:157]
	ds_read_b128 v[174:177], v210 offset:32768
	ds_read_b128 v[178:181], v210 offset:33792
	ds_read_b128 v[182:185], v210 offset:34816
	ds_read_b128 v[186:189], v210 offset:35840
	ds_read_b128 v[190:193], v210 offset:36864
	ds_read_b128 v[194:197], v210 offset:37888
	ds_read_b128 v[198:201], v210 offset:38912
	ds_read_b128 v[202:205], v210 offset:39936
	global_load_lds_dwordx4 v[222:223], off
	v_lshl_add_u64 v[222:223], s[8:9], 0, v[158:159]
	s_mov_b32 m0, s45
	s_nop 0
	global_load_lds_dwordx4 v[222:223], off
	s_waitcnt vmcnt(8)
	s_waitcnt lgkmcnt(0)
	s_setprio 1
	s_barrier
	v_mfma_f32_16x16x32_bf16 v[136:139], v[84:87], v[174:177], v[136:139]
	v_mfma_f32_16x16x32_bf16 v[132:135], v[120:123], v[174:177], v[132:135]
	v_mfma_f32_16x16x32_bf16 v[116:119], v[84:87], v[182:185], v[116:119]
	v_mfma_f32_16x16x32_bf16 v[112:115], v[120:123], v[182:185], v[112:115]
	v_mfma_f32_16x16x32_bf16 v[96:99], v[84:87], v[190:193], v[96:99]
	v_mfma_f32_16x16x32_bf16 v[92:95], v[120:123], v[190:193], v[92:95]
	v_mfma_f32_16x16x32_bf16 v[76:79], v[84:87], v[198:201], v[76:79]
	v_mfma_f32_16x16x32_bf16 v[72:75], v[120:123], v[198:201], v[72:75]
	v_mfma_f32_16x16x32_bf16 v[136:139], v[100:103], v[178:181], v[136:139]
	v_mfma_f32_16x16x32_bf16 v[132:135], v[140:143], v[178:181], v[132:135]
	v_mfma_f32_16x16x32_bf16 v[116:119], v[100:103], v[186:189], v[116:119]
	v_mfma_f32_16x16x32_bf16 v[112:115], v[140:143], v[186:189], v[112:115]
	v_mfma_f32_16x16x32_bf16 v[96:99], v[100:103], v[194:197], v[96:99]
	v_mfma_f32_16x16x32_bf16 v[92:95], v[140:143], v[194:197], v[92:95]
	v_mfma_f32_16x16x32_bf16 v[76:79], v[100:103], v[202:205], v[76:79]
	v_mfma_f32_16x16x32_bf16 v[72:75], v[140:143], v[202:205], v[72:75]
	v_mfma_f32_16x16x32_bf16 v[128:131], v[144:147], v[174:177], v[128:131]
	v_mfma_f32_16x16x32_bf16 v[124:127], v[152:155], v[174:177], v[124:127]
	v_mfma_f32_16x16x32_bf16 v[108:111], v[144:147], v[182:185], v[108:111]
	v_mfma_f32_16x16x32_bf16 v[104:107], v[152:155], v[182:185], v[104:107]
	v_mfma_f32_16x16x32_bf16 v[88:91], v[144:147], v[190:193], v[88:91]
	v_mfma_f32_16x16x32_bf16 v[80:83], v[152:155], v[190:193], v[80:83]
	v_mfma_f32_16x16x32_bf16 v[68:71], v[144:147], v[198:201], v[68:71]
	v_mfma_f32_16x16x32_bf16 v[64:67], v[152:155], v[198:201], v[64:67]
	v_mfma_f32_16x16x32_bf16 v[128:131], v[148:151], v[178:181], v[128:131]
	v_mfma_f32_16x16x32_bf16 v[124:127], v[170:173], v[178:181], v[124:127]
	v_mfma_f32_16x16x32_bf16 v[108:111], v[148:151], v[186:189], v[108:111]
	v_mfma_f32_16x16x32_bf16 v[104:107], v[170:173], v[186:189], v[104:107]
	v_mfma_f32_16x16x32_bf16 v[88:91], v[148:151], v[194:197], v[88:91]
	v_mfma_f32_16x16x32_bf16 v[80:83], v[170:173], v[194:197], v[80:83]
	v_mfma_f32_16x16x32_bf16 v[68:71], v[148:151], v[202:205], v[68:71]
	v_mfma_f32_16x16x32_bf16 v[64:67], v[170:173], v[202:205], v[64:67]
	s_barrier
	s_setprio 0
	s_add_i32 s8, s84, s3
	v_lshl_add_u64 v[214:215], v[214:215], 0, s[20:21]
	s_mov_b32 m0, s8
	ds_read_b128 v[174:177], v210 offset:49152
	ds_read_b128 v[178:181], v210 offset:50176
	ds_read_b128 v[182:185], v210 offset:51200
	ds_read_b128 v[186:189], v210 offset:52224
	ds_read_b128 v[190:193], v210 offset:53248
	ds_read_b128 v[194:197], v210 offset:54272
	ds_read_b128 v[198:201], v210 offset:55296
	ds_read_b128 v[202:205], v210 offset:56320
	global_load_lds_dwordx4 v[214:215], off
	s_add_i32 m0, s8, 0x2000
	s_add_u32 s8, s38, 0x18080
	v_lshl_add_u64 v[214:215], v[216:217], 0, s[20:21]
	s_addc_u32 s9, s39, 0
	s_add_i32 s38, s85, s3
	global_load_lds_dwordx4 v[214:215], off
	v_lshl_add_u64 v[214:215], s[8:9], 0, v[156:157]
	s_mov_b32 m0, s38
	s_nop 0
	global_load_lds_dwordx4 v[214:215], off
	v_lshl_add_u64 v[214:215], s[8:9], 0, v[158:159]
	s_add_i32 m0, s38, 0x2000
	s_nop 0
	global_load_lds_dwordx4 v[214:215], off
	v_lshl_add_u64 v[214:215], v[218:219], 0, s[20:21]
	s_mov_b32 m0, s51
	s_nop 0
	global_load_lds_dwordx4 v[214:215], off
	v_lshl_add_u64 v[214:215], v[220:221], 0, s[20:21]
	s_mov_b32 m0, s52
	s_nop 0
	global_load_lds_dwordx4 v[214:215], off
	s_waitcnt vmcnt(8)
	s_waitcnt lgkmcnt(0)
	s_setprio 1
	s_barrier
	v_mfma_f32_16x16x32_bf16 v[60:63], v[84:87], v[174:177], v[60:63]
	v_mfma_f32_16x16x32_bf16 v[56:59], v[120:123], v[174:177], v[56:59]
	v_mfma_f32_16x16x32_bf16 v[44:47], v[84:87], v[182:185], v[44:47]
	v_mfma_f32_16x16x32_bf16 v[40:43], v[120:123], v[182:185], v[40:43]
	v_mfma_f32_16x16x32_bf16 v[28:31], v[84:87], v[190:193], v[28:31]
	v_mfma_f32_16x16x32_bf16 v[24:27], v[120:123], v[190:193], v[24:27]
	v_mfma_f32_16x16x32_bf16 v[12:15], v[84:87], v[198:201], v[12:15]
	v_mfma_f32_16x16x32_bf16 v[8:11], v[120:123], v[198:201], v[8:11]
	v_mfma_f32_16x16x32_bf16 v[60:63], v[100:103], v[178:181], v[60:63]
	v_mfma_f32_16x16x32_bf16 v[56:59], v[140:143], v[178:181], v[56:59]
	v_mfma_f32_16x16x32_bf16 v[44:47], v[100:103], v[186:189], v[44:47]
	v_mfma_f32_16x16x32_bf16 v[40:43], v[140:143], v[186:189], v[40:43]
	v_mfma_f32_16x16x32_bf16 v[28:31], v[100:103], v[194:197], v[28:31]
	v_mfma_f32_16x16x32_bf16 v[24:27], v[140:143], v[194:197], v[24:27]
	v_mfma_f32_16x16x32_bf16 v[12:15], v[100:103], v[202:205], v[12:15]
	v_mfma_f32_16x16x32_bf16 v[8:11], v[140:143], v[202:205], v[8:11]
	v_mfma_f32_16x16x32_bf16 v[52:55], v[144:147], v[174:177], v[52:55]
	v_mfma_f32_16x16x32_bf16 v[48:51], v[152:155], v[174:177], v[48:51]
	v_mfma_f32_16x16x32_bf16 v[36:39], v[144:147], v[182:185], v[36:39]
	v_mfma_f32_16x16x32_bf16 v[32:35], v[152:155], v[182:185], v[32:35]
	v_mfma_f32_16x16x32_bf16 v[20:23], v[144:147], v[190:193], v[20:23]
	v_mfma_f32_16x16x32_bf16 v[16:19], v[152:155], v[190:193], v[16:19]
	v_mfma_f32_16x16x32_bf16 v[4:7], v[144:147], v[198:201], v[4:7]
	v_mfma_f32_16x16x32_bf16 v[0:3], v[152:155], v[198:201], v[0:3]
	v_mfma_f32_16x16x32_bf16 v[52:55], v[148:151], v[178:181], v[52:55]
	v_mfma_f32_16x16x32_bf16 v[48:51], v[170:173], v[178:181], v[48:51]
	v_mfma_f32_16x16x32_bf16 v[36:39], v[148:151], v[186:189], v[36:39]
	v_mfma_f32_16x16x32_bf16 v[32:35], v[170:173], v[186:189], v[32:35]
	v_mfma_f32_16x16x32_bf16 v[20:23], v[148:151], v[194:197], v[20:23]
	v_mfma_f32_16x16x32_bf16 v[16:19], v[170:173], v[194:197], v[16:19]
	v_mfma_f32_16x16x32_bf16 v[4:7], v[148:151], v[202:205], v[4:7]
	v_mfma_f32_16x16x32_bf16 v[0:3], v[170:173], v[202:205], v[0:3]
	s_barrier
	s_setprio 0
	s_add_i32 s83, s83, 2
	s_add_u32 s81, s81, 0x100
	s_addc_u32 s82, s82, 0
	s_cmp_gt_u32 s83, 3
	s_mov_b64 s[8:9], s[6:7]
	s_cbranch_scc0 .LBB0_771
	s_and_b64 vcc, exec, s[30:31]
	s_cbranch_vccz .LBB0_774
	s_barrier

.LBB0_938:
	ds_read_b128 v[128:131], v175
	ds_read_b128 v[132:135], v175 offset:1024
	ds_read_b128 v[136:139], v175 offset:2048
	ds_read_b128 v[140:143], v175 offset:3072
	ds_read_b128 v[144:147], v176
	ds_read_b128 v[148:151], v176 offset:1024
	ds_read_b128 v[168:171], v176 offset:2048
	ds_read_b128 v[182:185], v176 offset:3072
	s_add_u32 s36, s6, 0xfffe0080
	s_addc_u32 s37, s7, -1
	s_cmp_eq_u32 s42, 4
	s_cselect_b32 s39, s9, s37
	s_cselect_b32 s38, s27, s36
	s_cselect_b32 s37, s23, s41
	s_cselect_b32 s36, s35, s40
	v_lshl_add_u64 v[218:219], s[6:7], 0, v[158:159]
	s_add_i32 m0, s48, 0xc000
	ds_read_b128 v[186:189], v177
	ds_read_b128 v[190:193], v177 offset:1024
	ds_read_b128 v[194:197], v177 offset:2048
	ds_read_b128 v[198:201], v177 offset:3072
	ds_read_b128 v[202:205], v177 offset:4096
	ds_read_b128 v[206:209], v177 offset:5120
	ds_read_b128 v[210:213], v177 offset:6144
	ds_read_b128 v[214:217], v177 offset:7168
	global_load_lds_dwordx4 v[218:219], off
	v_lshl_add_u64 v[218:219], s[6:7], 0, v[160:161]
	s_add_i32 m0, s48, 0xe000
	s_nop 0
	global_load_lds_dwordx4 v[218:219], off
	s_waitcnt vmcnt(8)
	s_waitcnt lgkmcnt(0)
	s_setprio 1
	s_barrier
	v_mfma_f32_16x16x32_bf16 v[124:127], v[128:131], v[186:189], v[124:127]
	v_mfma_f32_16x16x32_bf16 v[120:123], v[136:139], v[186:189], v[120:123]
	v_mfma_f32_16x16x32_bf16 v[112:115], v[128:131], v[194:197], v[112:115]
	v_mfma_f32_16x16x32_bf16 v[116:119], v[136:139], v[194:197], v[116:119]
	v_mfma_f32_16x16x32_bf16 v[96:99], v[128:131], v[202:205], v[96:99]
	v_mfma_f32_16x16x32_bf16 v[104:107], v[136:139], v[202:205], v[104:107]
	v_mfma_f32_16x16x32_bf16 v[76:79], v[128:131], v[210:213], v[76:79]
	v_mfma_f32_16x16x32_bf16 v[72:75], v[136:139], v[210:213], v[72:75]
	v_mfma_f32_16x16x32_bf16 v[124:127], v[132:135], v[190:193], v[124:127]
	v_mfma_f32_16x16x32_bf16 v[120:123], v[140:143], v[190:193], v[120:123]
	v_mfma_f32_16x16x32_bf16 v[112:115], v[132:135], v[198:201], v[112:115]
	v_mfma_f32_16x16x32_bf16 v[116:119], v[140:143], v[198:201], v[116:119]
	v_mfma_f32_16x16x32_bf16 v[96:99], v[132:135], v[206:209], v[96:99]
	v_mfma_f32_16x16x32_bf16 v[104:107], v[140:143], v[206:209], v[104:107]
	v_mfma_f32_16x16x32_bf16 v[76:79], v[132:135], v[214:217], v[76:79]
	v_mfma_f32_16x16x32_bf16 v[72:75], v[140:143], v[214:217], v[72:75]
	v_mfma_f32_16x16x32_bf16 v[108:111], v[144:147], v[186:189], v[108:111]
	v_mfma_f32_16x16x32_bf16 v[100:103], v[168:171], v[186:189], v[100:103]
	v_mfma_f32_16x16x32_bf16 v[88:91], v[144:147], v[194:197], v[88:91]
	v_mfma_f32_16x16x32_bf16 v[92:95], v[168:171], v[194:197], v[92:95]
	v_mfma_f32_16x16x32_bf16 v[84:87], v[144:147], v[202:205], v[84:87]
	v_mfma_f32_16x16x32_bf16 v[80:83], v[168:171], v[202:205], v[80:83]
	v_mfma_f32_16x16x32_bf16 v[68:71], v[144:147], v[210:213], v[68:71]
	v_mfma_f32_16x16x32_bf16 v[64:67], v[168:171], v[210:213], v[64:67]
	v_mfma_f32_16x16x32_bf16 v[108:111], v[148:151], v[190:193], v[108:111]
	v_mfma_f32_16x16x32_bf16 v[100:103], v[182:185], v[190:193], v[100:103]
	v_mfma_f32_16x16x32_bf16 v[88:91], v[148:151], v[198:201], v[88:91]
	v_mfma_f32_16x16x32_bf16 v[92:95], v[182:185], v[198:201], v[92:95]
	v_mfma_f32_16x16x32_bf16 v[84:87], v[148:151], v[206:209], v[84:87]
	v_mfma_f32_16x16x32_bf16 v[80:83], v[182:185], v[206:209], v[80:83]
	v_mfma_f32_16x16x32_bf16 v[68:71], v[148:151], v[214:217], v[68:71]
	v_mfma_f32_16x16x32_bf16 v[64:67], v[182:185], v[214:217], v[64:67]
	s_barrier
	s_setprio 0
	s_add_i32 s43, s72, s47
	v_lshl_add_u64 v[218:219], s[36:37], 0, v[152:153]
	s_mov_b32 m0, s43
	ds_read_b128 v[186:189], v177 offset:16384
	ds_read_b128 v[190:193], v177 offset:17408
	ds_read_b128 v[194:197], v177 offset:18432
	ds_read_b128 v[198:201], v177 offset:19456
	ds_read_b128 v[202:205], v177 offset:20480
	ds_read_b128 v[206:209], v177 offset:21504
	ds_read_b128 v[210:213], v177 offset:22528
	ds_read_b128 v[214:217], v177 offset:23552
	global_load_lds_dwordx4 v[218:219], off
	s_add_i32 m0, s43, 0x2000
	s_add_u32 s88, s36, 0x20000
	v_lshl_add_u64 v[220:221], s[36:37], 0, v[154:155]
	s_addc_u32 s89, s37, 0
	s_add_i32 s43, s73, s47
	global_load_lds_dwordx4 v[220:221], off
	v_lshl_add_u64 v[222:223], s[88:89], 0, v[152:153]
	s_mov_b32 m0, s43
	v_lshl_add_u64 v[224:225], s[38:39], 0, v[154:155]
	global_load_lds_dwordx4 v[222:223], off
	v_lshl_add_u64 v[222:223], s[88:89], 0, v[154:155]
	s_add_i32 m0, s43, 0x2000
	s_nop 0
	global_load_lds_dwordx4 v[222:223], off
	v_lshl_add_u64 v[222:223], s[38:39], 0, v[152:153]
	s_mov_b32 m0, s48
	s_nop 0
	global_load_lds_dwordx4 v[222:223], off
	s_mov_b32 m0, s49
	s_nop 0
	global_load_lds_dwordx4 v[224:225], off
	s_waitcnt vmcnt(8)
	s_waitcnt lgkmcnt(0)
	s_setprio 1
	s_barrier
	v_mfma_f32_16x16x32_bf16 v[60:63], v[128:131], v[186:189], v[60:63]
	v_mfma_f32_16x16x32_bf16 v[56:59], v[136:139], v[186:189], v[56:59]
	v_mfma_f32_16x16x32_bf16 v[44:47], v[128:131], v[194:197], v[44:47]
	v_mfma_f32_16x16x32_bf16 v[40:43], v[136:139], v[194:197], v[40:43]
	v_mfma_f32_16x16x32_bf16 v[28:31], v[128:131], v[202:205], v[28:31]
	v_mfma_f32_16x16x32_bf16 v[24:27], v[136:139], v[202:205], v[24:27]
	v_mfma_f32_16x16x32_bf16 v[12:15], v[128:131], v[210:213], v[12:15]
	v_mfma_f32_16x16x32_bf16 v[8:11], v[136:139], v[210:213], v[8:11]
	v_mfma_f32_16x16x32_bf16 v[60:63], v[132:135], v[190:193], v[60:63]
	v_mfma_f32_16x16x32_bf16 v[56:59], v[140:143], v[190:193], v[56:59]
	v_mfma_f32_16x16x32_bf16 v[44:47], v[132:135], v[198:201], v[44:47]
	v_mfma_f32_16x16x32_bf16 v[40:43], v[140:143], v[198:201], v[40:43]
	v_mfma_f32_16x16x32_bf16 v[28:31], v[132:135], v[206:209], v[28:31]
	v_mfma_f32_16x16x32_bf16 v[24:27], v[140:143], v[206:209], v[24:27]
	v_mfma_f32_16x16x32_bf16 v[12:15], v[132:135], v[214:217], v[12:15]
	v_mfma_f32_16x16x32_bf16 v[8:11], v[140:143], v[214:217], v[8:11]
	v_mfma_f32_16x16x32_bf16 v[52:55], v[144:147], v[186:189], v[52:55]
	v_mfma_f32_16x16x32_bf16 v[48:51], v[168:171], v[186:189], v[48:51]
	v_mfma_f32_16x16x32_bf16 v[36:39], v[144:147], v[194:197], v[36:39]
	v_mfma_f32_16x16x32_bf16 v[32:35], v[168:171], v[194:197], v[32:35]
	v_mfma_f32_16x16x32_bf16 v[20:23], v[144:147], v[202:205], v[20:23]
	v_mfma_f32_16x16x32_bf16 v[16:19], v[168:171], v[202:205], v[16:19]
	v_mfma_f32_16x16x32_bf16 v[4:7], v[144:147], v[210:213], v[4:7]
	v_mfma_f32_16x16x32_bf16 v[0:3], v[168:171], v[210:213], v[0:3]
	v_mfma_f32_16x16x32_bf16 v[52:55], v[148:151], v[190:193], v[52:55]
	v_mfma_f32_16x16x32_bf16 v[48:51], v[182:185], v[190:193], v[48:51]
	v_mfma_f32_16x16x32_bf16 v[36:39], v[148:151], v[198:201], v[36:39]
	v_mfma_f32_16x16x32_bf16 v[32:35], v[182:185], v[198:201], v[32:35]
	v_mfma_f32_16x16x32_bf16 v[20:23], v[148:151], v[206:209], v[20:23]
	v_mfma_f32_16x16x32_bf16 v[16:19], v[182:185], v[206:209], v[16:19]
	v_mfma_f32_16x16x32_bf16 v[4:7], v[148:151], v[214:217], v[4:7]
	v_mfma_f32_16x16x32_bf16 v[0:3], v[182:185], v[214:217], v[0:3]
	s_barrier
	s_setprio 0
	s_add_i32 s43, 0, 0x18000
	s_add_i32 s88, 0, 0x1c000
	v_add_u32_e32 v140, s43, v173
	v_add_u32_e32 v156, s88, v173
	ds_read_b128 v[128:131], v140
	ds_read_b128 v[132:135], v140 offset:1024
	ds_read_b128 v[136:139], v140 offset:2048
	ds_read_b128 v[140:143], v140 offset:3072
	ds_read_b128 v[144:147], v156
	ds_read_b128 v[148:151], v156 offset:1024
	ds_read_b128 v[168:171], v156 offset:2048
	ds_read_b128 v[182:185], v156 offset:3072
	s_add_u32 s38, s38, 0x20000
	s_addc_u32 s39, s39, 0
	s_mov_b32 m0, s50
	v_lshl_add_u64 v[226:227], s[38:39], 0, v[152:153]
	ds_read_b128 v[186:189], v177 offset:32768
	ds_read_b128 v[190:193], v177 offset:33792
	ds_read_b128 v[194:197], v177 offset:34816
	ds_read_b128 v[198:201], v177 offset:35840
	ds_read_b128 v[202:205], v177 offset:36864
	ds_read_b128 v[206:209], v177 offset:37888
	ds_read_b128 v[210:213], v177 offset:38912
	ds_read_b128 v[214:217], v177 offset:39936
	global_load_lds_dwordx4 v[226:227], off
	v_lshl_add_u64 v[226:227], s[38:39], 0, v[154:155]
	s_mov_b32 m0, s51
	s_nop 0
	global_load_lds_dwordx4 v[226:227], off
	s_waitcnt vmcnt(8)
	s_waitcnt lgkmcnt(0)
	s_setprio 1
	s_barrier
	v_mfma_f32_16x16x32_bf16 v[124:127], v[128:131], v[186:189], v[124:127]
	v_mfma_f32_16x16x32_bf16 v[120:123], v[136:139], v[186:189], v[120:123]
	v_mfma_f32_16x16x32_bf16 v[112:115], v[128:131], v[194:197], v[112:115]
	v_mfma_f32_16x16x32_bf16 v[116:119], v[136:139], v[194:197], v[116:119]
	v_mfma_f32_16x16x32_bf16 v[96:99], v[128:131], v[202:205], v[96:99]
	v_mfma_f32_16x16x32_bf16 v[104:107], v[136:139], v[202:205], v[104:107]
	v_mfma_f32_16x16x32_bf16 v[76:79], v[128:131], v[210:213], v[76:79]
	v_mfma_f32_16x16x32_bf16 v[72:75], v[136:139], v[210:213], v[72:75]
	v_mfma_f32_16x16x32_bf16 v[124:127], v[132:135], v[190:193], v[124:127]
	v_mfma_f32_16x16x32_bf16 v[120:123], v[140:143], v[190:193], v[120:123]
	v_mfma_f32_16x16x32_bf16 v[112:115], v[132:135], v[198:201], v[112:115]
	v_mfma_f32_16x16x32_bf16 v[116:119], v[140:143], v[198:201], v[116:119]
	v_mfma_f32_16x16x32_bf16 v[96:99], v[132:135], v[206:209], v[96:99]
	v_mfma_f32_16x16x32_bf16 v[104:107], v[140:143], v[206:209], v[104:107]
	v_mfma_f32_16x16x32_bf16 v[76:79], v[132:135], v[214:217], v[76:79]
	v_mfma_f32_16x16x32_bf16 v[72:75], v[140:143], v[214:217], v[72:75]
	v_mfma_f32_16x16x32_bf16 v[108:111], v[144:147], v[186:189], v[108:111]
	v_mfma_f32_16x16x32_bf16 v[100:103], v[168:171], v[186:189], v[100:103]
	v_mfma_f32_16x16x32_bf16 v[88:91], v[144:147], v[194:197], v[88:91]
	v_mfma_f32_16x16x32_bf16 v[92:95], v[168:171], v[194:197], v[92:95]
	v_mfma_f32_16x16x32_bf16 v[84:87], v[144:147], v[202:205], v[84:87]
	v_mfma_f32_16x16x32_bf16 v[80:83], v[168:171], v[202:205], v[80:83]
	v_mfma_f32_16x16x32_bf16 v[68:71], v[144:147], v[210:213], v[68:71]
	v_mfma_f32_16x16x32_bf16 v[64:67], v[168:171], v[210:213], v[64:67]
	v_mfma_f32_16x16x32_bf16 v[108:111], v[148:151], v[190:193], v[108:111]
	v_mfma_f32_16x16x32_bf16 v[100:103], v[182:185], v[190:193], v[100:103]
	v_mfma_f32_16x16x32_bf16 v[88:91], v[148:151], v[198:201], v[88:91]
	v_mfma_f32_16x16x32_bf16 v[92:95], v[182:185], v[198:201], v[92:95]
	v_mfma_f32_16x16x32_bf16 v[84:87], v[148:151], v[206:209], v[84:87]
	v_mfma_f32_16x16x32_bf16 v[80:83], v[182:185], v[206:209], v[80:83]
	v_mfma_f32_16x16x32_bf16 v[68:71], v[148:151], v[214:217], v[68:71]
	v_mfma_f32_16x16x32_bf16 v[64:67], v[182:185], v[214:217], v[64:67]
	s_barrier
	s_setprio 0
	s_add_i32 s38, s43, s47
	v_lshl_add_u64 v[218:219], v[218:219], 0, s[16:17]
	s_mov_b32 m0, s38
	ds_read_b128 v[186:189], v177 offset:49152
	ds_read_b128 v[190:193], v177 offset:50176
	ds_read_b128 v[194:197], v177 offset:51200
	ds_read_b128 v[198:201], v177 offset:52224
	ds_read_b128 v[202:205], v177 offset:53248
	ds_read_b128 v[206:209], v177 offset:54272
	ds_read_b128 v[210:213], v177 offset:55296
	ds_read_b128 v[214:217], v177 offset:56320
	global_load_lds_dwordx4 v[218:219], off
	s_add_i32 m0, s38, 0x2000
	s_add_u32 s36, s36, 0x20080
	v_lshl_add_u64 v[218:219], v[220:221], 0, s[16:17]
	s_addc_u32 s37, s37, 0
	s_add_i32 s38, s88, s47
	global_load_lds_dwordx4 v[218:219], off
	v_lshl_add_u64 v[218:219], s[36:37], 0, v[152:153]
	s_mov_b32 m0, s38
	s_nop 0
	global_load_lds_dwordx4 v[218:219], off
	v_lshl_add_u64 v[218:219], s[36:37], 0, v[154:155]
	s_add_i32 m0, s38, 0x2000
	s_nop 0
	global_load_lds_dwordx4 v[218:219], off
	v_lshl_add_u64 v[218:219], v[222:223], 0, s[16:17]
	s_mov_b32 m0, s61
	s_nop 0
	global_load_lds_dwordx4 v[218:219], off
	v_lshl_add_u64 v[218:219], v[224:225], 0, s[16:17]
	s_mov_b32 m0, s62
	s_nop 0
	global_load_lds_dwordx4 v[218:219], off
	s_waitcnt vmcnt(8)
	s_waitcnt lgkmcnt(0)
	s_setprio 1
	s_barrier
	v_mfma_f32_16x16x32_bf16 v[60:63], v[128:131], v[186:189], v[60:63]
	v_mfma_f32_16x16x32_bf16 v[56:59], v[136:139], v[186:189], v[56:59]
	v_mfma_f32_16x16x32_bf16 v[44:47], v[128:131], v[194:197], v[44:47]
	v_mfma_f32_16x16x32_bf16 v[40:43], v[136:139], v[194:197], v[40:43]
	v_mfma_f32_16x16x32_bf16 v[28:31], v[128:131], v[202:205], v[28:31]
	v_mfma_f32_16x16x32_bf16 v[24:27], v[136:139], v[202:205], v[24:27]
	v_mfma_f32_16x16x32_bf16 v[12:15], v[128:131], v[210:213], v[12:15]
	v_mfma_f32_16x16x32_bf16 v[8:11], v[136:139], v[210:213], v[8:11]
	v_mfma_f32_16x16x32_bf16 v[60:63], v[132:135], v[190:193], v[60:63]
	v_mfma_f32_16x16x32_bf16 v[56:59], v[140:143], v[190:193], v[56:59]
	v_mfma_f32_16x16x32_bf16 v[44:47], v[132:135], v[198:201], v[44:47]
	v_mfma_f32_16x16x32_bf16 v[40:43], v[140:143], v[198:201], v[40:43]
	v_mfma_f32_16x16x32_bf16 v[28:31], v[132:135], v[206:209], v[28:31]
	v_mfma_f32_16x16x32_bf16 v[24:27], v[140:143], v[206:209], v[24:27]
	v_mfma_f32_16x16x32_bf16 v[12:15], v[132:135], v[214:217], v[12:15]
	v_mfma_f32_16x16x32_bf16 v[8:11], v[140:143], v[214:217], v[8:11]
	v_mfma_f32_16x16x32_bf16 v[52:55], v[144:147], v[186:189], v[52:55]
	v_mfma_f32_16x16x32_bf16 v[48:51], v[168:171], v[186:189], v[48:51]
	v_mfma_f32_16x16x32_bf16 v[36:39], v[144:147], v[194:197], v[36:39]
	v_mfma_f32_16x16x32_bf16 v[32:35], v[168:171], v[194:197], v[32:35]
	v_mfma_f32_16x16x32_bf16 v[20:23], v[144:147], v[202:205], v[20:23]
	v_mfma_f32_16x16x32_bf16 v[16:19], v[168:171], v[202:205], v[16:19]
	v_mfma_f32_16x16x32_bf16 v[4:7], v[144:147], v[210:213], v[4:7]
	v_mfma_f32_16x16x32_bf16 v[0:3], v[168:171], v[210:213], v[0:3]
	v_mfma_f32_16x16x32_bf16 v[52:55], v[148:151], v[190:193], v[52:55]
	v_mfma_f32_16x16x32_bf16 v[48:51], v[182:185], v[190:193], v[48:51]
	v_mfma_f32_16x16x32_bf16 v[36:39], v[148:151], v[198:201], v[36:39]
	v_mfma_f32_16x16x32_bf16 v[32:35], v[182:185], v[198:201], v[32:35]
	v_mfma_f32_16x16x32_bf16 v[20:23], v[148:151], v[206:209], v[20:23]
	v_mfma_f32_16x16x32_bf16 v[16:19], v[182:185], v[206:209], v[16:19]
	v_mfma_f32_16x16x32_bf16 v[4:7], v[148:151], v[214:217], v[4:7]
	v_mfma_f32_16x16x32_bf16 v[0:3], v[182:185], v[214:217], v[0:3]
	s_barrier
	s_setprio 0
	s_add_i32 s42, s42, 2
	s_add_u32 s6, s6, 0x100
	s_addc_u32 s7, s7, 0
	s_add_u32 s40, s40, 0x100
	s_addc_u32 s41, s41, 0
	s_cmp_gt_u32 s42, 5
	s_cbranch_scc0 .LBB0_938
	s_and_b64 vcc, exec, s[18:19]
	s_cbranch_vccz .LBB0_941
	s_barrier
